# K-loop LDS read rebalancing: phase-5 B fragment reads issued one phase early (all loops but int8), phase-1 B reads one phase early in bf16 loops (new regs v232-247), counted vmcnt(10) covers them
# speedup vs baseline: 1.0090x; 1.0012x over previous
; #define G_STAGE(bufoff, gbase, voff) do { _Pragma("unroll") for (int _i = 0; _i < 2; ++_i) \
;         __builtin_amdgcn_global_load_lds((const unsigned*)((const char*)(gbase) + (voff)[_i]), (LAS unsigned*)(lds + (bufoff) + ldsw + _i * 8192), 16, 0, 0); } while (0)
; #define G_WAIT_V(n) asm volatile("s_waitcnt vmcnt(" #n ")" ::: "memory")
; #define G_WAIT_L(n) asm volatile("s_waitcnt lgkmcnt(" #n ")" ::: "memory")
; #define G_BAR __builtin_amdgcn_s_barrier()
; #define G_SCHED __builtin_amdgcn_sched_barrier(0)
; template <int MODE  , class Epi, class Sched>
; __device__ __forceinline__ void gemm_phase(LAS unsigned char* lds, const GemmDesc g, const Sched& S, const Epi& E) {
;     ...
;             const bool last = (t == nt - 2);
;             const char* a1 = cA + (size_t)(t + 1) * kstep;
;             const char* a2 = last ? nA : cA + (size_t)(t + 2) * kstep; const char* b2 = last ? nB : cB + (size_t)(t + 2) * kstep;
;             const char* a3 = a2 + kstep; const char* b3 = b2 + kstep;
;             G_LDB(B0, 0, 0); G_SCHED; G_LDA(At, 0, 0); G_STAGE(G_SA(1, 1), a1 + hstepA, voffA);
;             G_WAIT_L(8); G_BAR; G_WAIT_L(0); G_MMA(0, 0, At, B0); G_BAR; G_SCHED;
;             G_LDB(B1, 0, 1); G_STAGE(G_SB(0, 0), b2, voffB);
;             G_BAR; G_WAIT_L(0); G_MMA(0, 1, At, B1); G_BAR;
;             G_LDA(At, 0, 1); G_STAGE(G_SA(0, 0), a2, voffA);
;             G_BAR; G_WAIT_L(0); G_MMA(1, 0, At, B0); G_BAR; G_SCHED;
;             G_STAGE(G_SB(0, 1), b2 + hstepB, voffB);
;             G_WAIT_V(6); G_BAR; G_MMA(1, 1, At, B1); G_BAR;
;             G_LDB(B0, 1, 0); G_SCHED; G_LDA(At, 1, 0); G_STAGE(G_SA(0, 1), a2 + hstepA, voffA);
;             G_WAIT_L(8); G_BAR; G_WAIT_L(0); G_MMA(0, 0, At, B0); G_BAR; G_SCHED;
.Lnodb_p1b:
.LBB0_737:
	ds_read_b128 v[2:5], v168
	ds_read_b128 v[6:9], v168 offset:1024
	ds_read_b128 v[10:13], v168 offset:2048
	ds_read_b128 v[14:17], v168 offset:3072
	s_add_u32 s46, s50, 0x100
	s_addc_u32 s47, s51, 0
	s_cmp_eq_u32 s79, 12
	s_cselect_b32 s55, s45, s47
	s_cselect_b32 s54, s44, s46
	s_cselect_b32 s53, s3, s78
	s_cselect_b32 s52, s2, s77
	s_add_u32 s98, s50, 0x44080
	s_addc_u32 s99, s51, 0
	s_add_i32 m0, s62, 0xc000
	ds_read_b128 v[174:177], v169
	ds_read_b128 v[178:181], v169 offset:1024
	ds_read_b128 v[182:185], v169 offset:2048
	ds_read_b128 v[186:189], v169 offset:3072
	ds_read_b128 v[192:195], v169 offset:4096
	ds_read_b128 v[196:199], v169 offset:5120
	ds_read_b128 v[200:203], v169 offset:6144
	ds_read_b128 v[204:207], v169 offset:7168
	global_load_lds_dwordx4 v152, s[98:99]
	s_add_i32 m0, s62, 0xe000
	s_nop 0
	global_load_lds_dwordx4 v148, s[98:99]
	s_waitcnt lgkmcnt(8)
	s_barrier
	s_waitcnt lgkmcnt(0)
	s_setprio 1
	s_waitcnt lgkmcnt(0)
	v_mfma_scale_f32_16x16x128_f8f6f4 v[142:145], v[2:9], v[174:181], v[142:145], v170, v170 op_sel_hi:[0,0,0]
	v_mfma_scale_f32_16x16x128_f8f6f4 v[138:141], v[10:17], v[174:181], v[138:141], v170, v170 op_sel_hi:[0,0,0]
	v_mfma_scale_f32_16x16x128_f8f6f4 v[126:129], v[2:9], v[182:189], v[126:129], v170, v170 op_sel_hi:[0,0,0]
	v_mfma_scale_f32_16x16x128_f8f6f4 v[122:125], v[10:17], v[182:189], v[122:125], v170, v170 op_sel_hi:[0,0,0]
	v_mfma_scale_f32_16x16x128_f8f6f4 v[110:113], v[2:9], v[192:199], v[110:113], v170, v170 op_sel_hi:[0,0,0]
	v_mfma_scale_f32_16x16x128_f8f6f4 v[106:109], v[10:17], v[192:199], v[106:109], v170, v170 op_sel_hi:[0,0,0]
	v_mfma_scale_f32_16x16x128_f8f6f4 v[94:97], v[2:9], v[200:207], v[94:97], v170, v170 op_sel_hi:[0,0,0]
	v_mfma_scale_f32_16x16x128_f8f6f4 v[90:93], v[10:17], v[200:207], v[90:93], v170, v170 op_sel_hi:[0,0,0]
	s_setprio 0
	s_barrier
	s_add_i32 s0, s69, s60
	s_mov_b32 m0, s0
	ds_read_b128 v[208:211], v171
	ds_read_b128 v[212:215], v171 offset:1024
	ds_read_b128 v[216:219], v171 offset:2048
	ds_read_b128 v[220:223], v171 offset:3072
	global_load_lds_dwordx4 v150, s[52:53]
	s_add_i32 m0, s0, 0x2000
	s_nop 0
	global_load_lds_dwordx4 v146, s[52:53]
	s_barrier
	s_waitcnt lgkmcnt(0)
	s_setprio 1
	s_waitcnt lgkmcnt(0)
	v_mfma_scale_f32_16x16x128_f8f6f4 v[134:137], v[208:215], v[174:181], v[134:137], v170, v170 op_sel_hi:[0,0,0]
	v_mfma_scale_f32_16x16x128_f8f6f4 v[130:133], v[216:223], v[174:181], v[130:133], v170, v170 op_sel_hi:[0,0,0]
	v_mfma_scale_f32_16x16x128_f8f6f4 v[118:121], v[208:215], v[182:189], v[118:121], v170, v170 op_sel_hi:[0,0,0]
	v_mfma_scale_f32_16x16x128_f8f6f4 v[114:117], v[216:223], v[182:189], v[114:117], v170, v170 op_sel_hi:[0,0,0]
	v_mfma_scale_f32_16x16x128_f8f6f4 v[102:105], v[208:215], v[192:199], v[102:105], v170, v170 op_sel_hi:[0,0,0]
	v_mfma_scale_f32_16x16x128_f8f6f4 v[98:101], v[216:223], v[192:199], v[98:101], v170, v170 op_sel_hi:[0,0,0]
	v_mfma_scale_f32_16x16x128_f8f6f4 v[86:89], v[208:215], v[200:207], v[86:89], v170, v170 op_sel_hi:[0,0,0]
	v_mfma_scale_f32_16x16x128_f8f6f4 v[82:85], v[216:223], v[200:207], v[82:85], v170, v170 op_sel_hi:[0,0,0]
	s_setprio 0
	s_mov_b32 m0, s62
	s_barrier
	ds_read_b128 v[174:177], v169 offset:16384
	ds_read_b128 v[178:181], v169 offset:17408
	ds_read_b128 v[182:185], v169 offset:18432
	ds_read_b128 v[186:189], v169 offset:19456
	ds_read_b128 v[192:195], v169 offset:20480
	ds_read_b128 v[196:199], v169 offset:21504
	ds_read_b128 v[200:203], v169 offset:22528
	ds_read_b128 v[204:207], v169 offset:23552
	global_load_lds_dwordx4 v152, s[54:55]
	s_mov_b32 m0, s63
	s_nop 0
	global_load_lds_dwordx4 v148, s[54:55]
	s_waitcnt vmcnt(10)
	s_barrier
	s_waitcnt lgkmcnt(0)
	s_setprio 1
	s_waitcnt lgkmcnt(0)
	v_mfma_scale_f32_16x16x128_f8f6f4 v[78:81], v[2:9], v[174:181], v[78:81], v170, v170 op_sel_hi:[0,0,0]
	v_mfma_scale_f32_16x16x128_f8f6f4 v[74:77], v[10:17], v[174:181], v[74:77], v170, v170 op_sel_hi:[0,0,0]
	v_mfma_scale_f32_16x16x128_f8f6f4 v[62:65], v[2:9], v[182:189], v[62:65], v170, v170 op_sel_hi:[0,0,0]
	v_mfma_scale_f32_16x16x128_f8f6f4 v[58:61], v[10:17], v[182:189], v[58:61], v170, v170 op_sel_hi:[0,0,0]
	v_mfma_scale_f32_16x16x128_f8f6f4 v[46:49], v[2:9], v[192:199], v[46:49], v170, v170 op_sel_hi:[0,0,0]
	v_mfma_scale_f32_16x16x128_f8f6f4 v[42:45], v[10:17], v[192:199], v[42:45], v170, v170 op_sel_hi:[0,0,0]
	v_mfma_scale_f32_16x16x128_f8f6f4 v[30:33], v[2:9], v[200:207], v[30:33], v170, v170 op_sel_hi:[0,0,0]
	v_mfma_scale_f32_16x16x128_f8f6f4 v[26:29], v[10:17], v[200:207], v[26:29], v170, v170 op_sel_hi:[0,0,0]
	s_setprio 0
	s_barrier
	v_add_u32_e32 v14, 0x18000, v166
	ds_read_b128 v[2:5], v14
	ds_read_b128 v[6:9], v14 offset:1024
	ds_read_b128 v[10:13], v14 offset:2048
	ds_read_b128 v[14:17], v14 offset:3072
	s_add_u32 s0, s52, 0x44000
	s_addc_u32 s1, s53, 0
	s_add_i32 s10, s70, s60
	s_mov_b32 m0, s10
	s_nop 0
	global_load_lds_dwordx4 v150, s[0:1]
	s_add_i32 m0, s10, 0x2000
	s_nop 0
	global_load_lds_dwordx4 v146, s[0:1]
	s_waitcnt vmcnt(6)
	s_barrier
	s_setprio 1
	v_mfma_scale_f32_16x16x128_f8f6f4 v[70:73], v[208:215], v[174:181], v[70:73], v170, v170 op_sel_hi:[0,0,0]
	v_mfma_scale_f32_16x16x128_f8f6f4 v[66:69], v[216:223], v[174:181], v[66:69], v170, v170 op_sel_hi:[0,0,0]
	v_mfma_scale_f32_16x16x128_f8f6f4 v[54:57], v[208:215], v[182:189], v[54:57], v170, v170 op_sel_hi:[0,0,0]
	v_mfma_scale_f32_16x16x128_f8f6f4 v[50:53], v[216:223], v[182:189], v[50:53], v170, v170 op_sel_hi:[0,0,0]
	v_mfma_scale_f32_16x16x128_f8f6f4 v[38:41], v[208:215], v[192:199], v[38:41], v170, v170 op_sel_hi:[0,0,0]
	v_mfma_scale_f32_16x16x128_f8f6f4 v[34:37], v[216:223], v[192:199], v[34:37], v170, v170 op_sel_hi:[0,0,0]
	v_mfma_scale_f32_16x16x128_f8f6f4 v[22:25], v[208:215], v[200:207], v[22:25], v170, v170 op_sel_hi:[0,0,0]
	v_mfma_scale_f32_16x16x128_f8f6f4 v[18:21], v[216:223], v[200:207], v[18:21], v170, v170 op_sel_hi:[0,0,0]
	s_setprio 0
	s_add_i32 s10, 0, 0x18000
	s_barrier
; #define G_STAGE(bufoff, gbase, voff) do { _Pragma("unroll") for (int _i = 0; _i < 2; ++_i) \
;         __builtin_amdgcn_global_load_lds((const unsigned*)((const char*)(gbase) + (voff)[_i]), (LAS unsigned*)(lds + (bufoff) + ldsw + _i * 8192), 16, 0, 0); } while (0)
; #define G_WAIT_V(n) asm volatile("s_waitcnt vmcnt(" #n ")" ::: "memory")
; #define G_WAIT_L(n) asm volatile("s_waitcnt lgkmcnt(" #n ")" ::: "memory")
; #define G_BAR __builtin_amdgcn_s_barrier()
; #define G_SCHED __builtin_amdgcn_sched_barrier(0)
; template <int MODE  , class Epi, class Sched>
; __device__ __forceinline__ void gemm_phase(LAS unsigned char* lds, const GemmDesc g, const Sched& S, const Epi& E) {
;     ...
;             G_LDB(B0, 1, 0); G_SCHED; G_LDA(At, 1, 0); G_STAGE(G_SA(0, 1), a2 + hstepA, voffA);
;             G_WAIT_L(8); G_BAR; G_WAIT_L(0); G_MMA(0, 0, At, B0); G_BAR; G_SCHED;
;             G_LDB(B1, 1, 1); G_STAGE(G_SB(1, 0), b3, voffB);
;             G_BAR; G_WAIT_L(0); G_MMA(0, 1, At, B1); G_BAR;
;             G_LDA(At, 1, 1); G_STAGE(G_SA(1, 0), a3, voffA);
;             G_BAR; G_WAIT_L(0); G_MMA(1, 0, At, B0); G_BAR; G_SCHED;
;             G_STAGE(G_SB(1, 1), b3 + hstepB, voffB);
;             G_WAIT_V(6); G_BAR; G_MMA(1, 1, At, B1); G_BAR;
;         }
	s_add_u32 s0, s54, 0x44000
	s_addc_u32 s1, s55, 0
	s_mov_b32 m0, s64
	ds_read_b128 v[174:177], v169 offset:32768
	ds_read_b128 v[178:181], v169 offset:33792
	ds_read_b128 v[182:185], v169 offset:34816
	ds_read_b128 v[186:189], v169 offset:35840
	ds_read_b128 v[192:195], v169 offset:36864
	ds_read_b128 v[196:199], v169 offset:37888
	ds_read_b128 v[200:203], v169 offset:38912
	ds_read_b128 v[204:207], v169 offset:39936
	global_load_lds_dwordx4 v152, s[0:1]
	s_mov_b32 m0, s65
	s_nop 0
	global_load_lds_dwordx4 v148, s[0:1]
	s_waitcnt lgkmcnt(8)
	s_barrier
	s_waitcnt lgkmcnt(0)
	s_setprio 1
	s_waitcnt lgkmcnt(0)
	v_mfma_scale_f32_16x16x128_f8f6f4 v[142:145], v[2:9], v[174:181], v[142:145], v170, v170 op_sel_hi:[0,0,0]
	v_mfma_scale_f32_16x16x128_f8f6f4 v[138:141], v[10:17], v[174:181], v[138:141], v170, v170 op_sel_hi:[0,0,0]
	v_mfma_scale_f32_16x16x128_f8f6f4 v[126:129], v[2:9], v[182:189], v[126:129], v170, v170 op_sel_hi:[0,0,0]
	v_mfma_scale_f32_16x16x128_f8f6f4 v[122:125], v[10:17], v[182:189], v[122:125], v170, v170 op_sel_hi:[0,0,0]
	v_mfma_scale_f32_16x16x128_f8f6f4 v[110:113], v[2:9], v[192:199], v[110:113], v170, v170 op_sel_hi:[0,0,0]
	v_mfma_scale_f32_16x16x128_f8f6f4 v[106:109], v[10:17], v[192:199], v[106:109], v170, v170 op_sel_hi:[0,0,0]
	v_mfma_scale_f32_16x16x128_f8f6f4 v[94:97], v[2:9], v[200:207], v[94:97], v170, v170 op_sel_hi:[0,0,0]
	v_mfma_scale_f32_16x16x128_f8f6f4 v[90:93], v[10:17], v[200:207], v[90:93], v170, v170 op_sel_hi:[0,0,0]
	s_setprio 0
	s_barrier
	s_add_i32 s11, 0, 0x1c000
	s_add_i32 s0, s10, s60
	v_add_u32_e32 v173, s11, v166
	s_add_u32 s98, s52, 0x80
	s_addc_u32 s99, s53, 0
	s_mov_b32 m0, s0
	ds_read_b128 v[208:211], v173
	ds_read_b128 v[212:215], v173 offset:1024
	ds_read_b128 v[216:219], v173 offset:2048
	ds_read_b128 v[220:223], v173 offset:3072
	global_load_lds_dwordx4 v150, s[98:99]
	s_add_i32 m0, s0, 0x2000
	s_nop 0
	global_load_lds_dwordx4 v146, s[98:99]
	s_barrier
	s_waitcnt lgkmcnt(0)
	s_setprio 1
	s_waitcnt lgkmcnt(0)
	v_mfma_scale_f32_16x16x128_f8f6f4 v[134:137], v[208:215], v[174:181], v[134:137], v170, v170 op_sel_hi:[0,0,0]
	v_mfma_scale_f32_16x16x128_f8f6f4 v[130:133], v[216:223], v[174:181], v[130:133], v170, v170 op_sel_hi:[0,0,0]
	v_mfma_scale_f32_16x16x128_f8f6f4 v[118:121], v[208:215], v[182:189], v[118:121], v170, v170 op_sel_hi:[0,0,0]
	v_mfma_scale_f32_16x16x128_f8f6f4 v[114:117], v[216:223], v[182:189], v[114:117], v170, v170 op_sel_hi:[0,0,0]
	v_mfma_scale_f32_16x16x128_f8f6f4 v[102:105], v[208:215], v[192:199], v[102:105], v170, v170 op_sel_hi:[0,0,0]
	v_mfma_scale_f32_16x16x128_f8f6f4 v[98:101], v[216:223], v[192:199], v[98:101], v170, v170 op_sel_hi:[0,0,0]
	v_mfma_scale_f32_16x16x128_f8f6f4 v[86:89], v[208:215], v[200:207], v[86:89], v170, v170 op_sel_hi:[0,0,0]
	v_mfma_scale_f32_16x16x128_f8f6f4 v[82:85], v[216:223], v[200:207], v[82:85], v170, v170 op_sel_hi:[0,0,0]
	s_setprio 0
	s_mov_b32 m0, s67
	s_add_u32 s98, s54, 0x80
	s_addc_u32 s99, s55, 0
	s_barrier
	ds_read_b128 v[174:177], v169 offset:49152
	ds_read_b128 v[178:181], v169 offset:50176
	ds_read_b128 v[182:185], v169 offset:51200
	ds_read_b128 v[186:189], v169 offset:52224
	ds_read_b128 v[192:195], v169 offset:53248
	ds_read_b128 v[196:199], v169 offset:54272
	ds_read_b128 v[200:203], v169 offset:55296
	ds_read_b128 v[204:207], v169 offset:56320
	global_load_lds_dwordx4 v152, s[98:99]
	s_mov_b32 m0, s68
	s_nop 0
	global_load_lds_dwordx4 v148, s[98:99]
	s_barrier
	s_waitcnt lgkmcnt(0)
	s_setprio 1
	s_waitcnt lgkmcnt(0)
	v_mfma_scale_f32_16x16x128_f8f6f4 v[78:81], v[2:9], v[174:181], v[78:81], v170, v170 op_sel_hi:[0,0,0]
	v_mfma_scale_f32_16x16x128_f8f6f4 v[74:77], v[10:17], v[174:181], v[74:77], v170, v170 op_sel_hi:[0,0,0]
	v_mfma_scale_f32_16x16x128_f8f6f4 v[62:65], v[2:9], v[182:189], v[62:65], v170, v170 op_sel_hi:[0,0,0]
	v_mfma_scale_f32_16x16x128_f8f6f4 v[58:61], v[10:17], v[182:189], v[58:61], v170, v170 op_sel_hi:[0,0,0]
	v_mfma_scale_f32_16x16x128_f8f6f4 v[46:49], v[2:9], v[192:199], v[46:49], v170, v170 op_sel_hi:[0,0,0]
	v_mfma_scale_f32_16x16x128_f8f6f4 v[42:45], v[10:17], v[192:199], v[42:45], v170, v170 op_sel_hi:[0,0,0]
	v_mfma_scale_f32_16x16x128_f8f6f4 v[30:33], v[2:9], v[200:207], v[30:33], v170, v170 op_sel_hi:[0,0,0]
	v_mfma_scale_f32_16x16x128_f8f6f4 v[26:29], v[10:17], v[200:207], v[26:29], v170, v170 op_sel_hi:[0,0,0]
	s_setprio 0
	s_barrier
	s_add_u32 s0, s52, 0x44080
	s_addc_u32 s1, s53, 0
	s_add_i32 s10, s11, s60
	s_mov_b32 m0, s10
	s_nop 0
	global_load_lds_dwordx4 v150, s[0:1]
	s_add_i32 m0, s10, 0x2000
	s_nop 0
	global_load_lds_dwordx4 v146, s[0:1]
	s_waitcnt vmcnt(6)
	s_barrier
	s_setprio 1
	v_mfma_scale_f32_16x16x128_f8f6f4 v[70:73], v[208:215], v[174:181], v[70:73], v170, v170 op_sel_hi:[0,0,0]
	s_add_i32 s79, s79, 2
	s_add_u32 s77, s77, 0x100
	s_addc_u32 s78, s78, 0
	s_cmp_gt_u32 s79, 13
	s_mov_b64 s[50:51], s[46:47]
	v_mfma_scale_f32_16x16x128_f8f6f4 v[66:69], v[216:223], v[174:181], v[66:69], v170, v170 op_sel_hi:[0,0,0]
	v_mfma_scale_f32_16x16x128_f8f6f4 v[54:57], v[208:215], v[182:189], v[54:57], v170, v170 op_sel_hi:[0,0,0]
	v_mfma_scale_f32_16x16x128_f8f6f4 v[50:53], v[216:223], v[182:189], v[50:53], v170, v170 op_sel_hi:[0,0,0]
	v_mfma_scale_f32_16x16x128_f8f6f4 v[38:41], v[208:215], v[192:199], v[38:41], v170, v170 op_sel_hi:[0,0,0]
	v_mfma_scale_f32_16x16x128_f8f6f4 v[34:37], v[216:223], v[192:199], v[34:37], v170, v170 op_sel_hi:[0,0,0]
	v_mfma_scale_f32_16x16x128_f8f6f4 v[22:25], v[208:215], v[200:207], v[22:25], v170, v170 op_sel_hi:[0,0,0]
	v_mfma_scale_f32_16x16x128_f8f6f4 v[18:21], v[216:223], v[200:207], v[18:21], v170, v170 op_sel_hi:[0,0,0]
	s_setprio 0
	s_cbranch_scc1 .Lkdone_p1b
	s_barrier
	s_branch .LBB0_737

; #define G_STAGE(bufoff, gbase, voff) do { _Pragma("unroll") for (int _i = 0; _i < 2; ++_i) \
;         __builtin_amdgcn_global_load_lds((const unsigned*)((const char*)(gbase) + (voff)[_i]), (LAS unsigned*)(lds + (bufoff) + ldsw + _i * 8192), 16, 0, 0); } while (0)
; #define G_WAIT_V(n) asm volatile("s_waitcnt vmcnt(" #n ")" ::: "memory")
; #define G_WAIT_L(n) asm volatile("s_waitcnt lgkmcnt(" #n ")" ::: "memory")
; #define G_BAR __builtin_amdgcn_s_barrier()
; #define G_SCHED __builtin_amdgcn_sched_barrier(0)
; template <int MODE  , class Epi, class Sched>
; __device__ __forceinline__ void gemm_phase(LAS unsigned char* lds, const GemmDesc g, const Sched& S, const Epi& E) {
;     ...
;             const bool last = (t == nt - 2);
;             const char* a1 = cA + (size_t)(t + 1) * kstep;
;             const char* a2 = last ? nA : cA + (size_t)(t + 2) * kstep; const char* b2 = last ? nB : cB + (size_t)(t + 2) * kstep;
;             const char* a3 = a2 + kstep; const char* b3 = b2 + kstep;
;             G_LDB(B0, 0, 0); G_SCHED; G_LDA(At, 0, 0); G_STAGE(G_SA(1, 1), a1 + hstepA, voffA);
;             G_WAIT_L(8); G_BAR; G_WAIT_L(0); G_MMA(0, 0, At, B0); G_BAR; G_SCHED;
;             G_LDB(B1, 0, 1); G_STAGE(G_SB(0, 0), b2, voffB);
;             G_BAR; G_WAIT_L(0); G_MMA(0, 1, At, B1); G_BAR;
;             G_LDA(At, 0, 1); G_STAGE(G_SA(0, 0), a2, voffA);
;             G_BAR; G_WAIT_L(0); G_MMA(1, 0, At, B0); G_BAR; G_SCHED;
;             G_STAGE(G_SB(0, 1), b2 + hstepB, voffB);
;             G_WAIT_V(6); G_BAR; G_MMA(1, 1, At, B1); G_BAR;
.Lnodb_sa:
	v_add_u32_e32 v244, s58, v172
	ds_read_b128 v[232:235], v244
	ds_read_b128 v[236:239], v244 offset:1024
	ds_read_b128 v[240:243], v244 offset:2048
	ds_read_b128 v[244:247], v244 offset:3072
.LBB0_815:
	s_add_u32 s44, s42, 0x100
	s_addc_u32 s45, s43, 0
	s_cmp_eq_u32 s68, 12
	s_cselect_b32 s49, s35, s45
	s_cselect_b32 s48, s34, s44
	s_cselect_b32 s47, s3, s67
	s_cselect_b32 s46, s2, s21
	s_add_u32 s98, s42, 0x84080
	s_addc_u32 s99, s43, 0
	s_add_i32 m0, s52, 0xc000
	ds_read_b128 v[158:161], v174
	ds_read_b128 v[162:165], v174 offset:1024
	ds_read_b128 v[166:169], v174 offset:2048
	ds_read_b128 v[176:179], v174 offset:3072
	ds_read_b128 v[180:183], v174 offset:4096
	ds_read_b128 v[184:187], v174 offset:5120
	ds_read_b128 v[192:195], v174 offset:6144
	ds_read_b128 v[196:199], v174 offset:7168
	global_load_lds_dwordx4 v146, s[98:99]
	s_add_i32 m0, s52, 0xe000
	s_nop 0
	global_load_lds_dwordx4 v150, s[98:99]
	s_waitcnt lgkmcnt(8)
	s_barrier
	s_waitcnt lgkmcnt(0)
	s_setprio 1
	s_waitcnt lgkmcnt(0)
	v_mfma_f32_16x16x32_bf16 v[126:129], v[232:235], v[158:161], v[126:129]
	v_mfma_f32_16x16x32_bf16 v[122:125], v[240:243], v[158:161], v[122:125]
	v_mfma_f32_16x16x32_bf16 v[118:121], v[232:235], v[166:169], v[118:121]
	v_mfma_f32_16x16x32_bf16 v[114:117], v[240:243], v[166:169], v[114:117]
	v_mfma_f32_16x16x32_bf16 v[110:113], v[232:235], v[180:183], v[110:113]
	v_mfma_f32_16x16x32_bf16 v[106:109], v[240:243], v[180:183], v[106:109]
	v_mfma_f32_16x16x32_bf16 v[102:105], v[232:235], v[192:195], v[102:105]
	v_mfma_f32_16x16x32_bf16 v[98:101], v[240:243], v[192:195], v[98:101]
	v_mfma_f32_16x16x32_bf16 v[126:129], v[236:239], v[162:165], v[126:129]
	v_mfma_f32_16x16x32_bf16 v[122:125], v[244:247], v[162:165], v[122:125]
	v_mfma_f32_16x16x32_bf16 v[118:121], v[236:239], v[176:179], v[118:121]
	v_mfma_f32_16x16x32_bf16 v[114:117], v[244:247], v[176:179], v[114:117]
	v_mfma_f32_16x16x32_bf16 v[110:113], v[236:239], v[184:187], v[110:113]
	v_mfma_f32_16x16x32_bf16 v[106:109], v[244:247], v[184:187], v[106:109]
	v_mfma_f32_16x16x32_bf16 v[102:105], v[236:239], v[196:199], v[102:105]
	v_mfma_f32_16x16x32_bf16 v[98:101], v[244:247], v[196:199], v[98:101]
	s_setprio 0
	s_barrier
	v_add_u32_e32 v170, s59, v172
	s_add_i32 s0, s58, s51
	ds_read_b128 v[200:203], v170
	ds_read_b128 v[204:207], v170 offset:1024
	ds_read_b128 v[208:211], v170 offset:2048
	ds_read_b128 v[212:215], v170 offset:3072
	s_mov_b32 m0, s0
	s_nop 0
	global_load_lds_dwordx4 v148, s[46:47]
	s_add_i32 m0, s0, 0x2000
	s_nop 0
	global_load_lds_dwordx4 v152, s[46:47]
	s_barrier
	s_waitcnt lgkmcnt(0)
	s_setprio 1
	s_waitcnt lgkmcnt(0)
	v_mfma_f32_16x16x32_bf16 v[94:97], v[200:203], v[158:161], v[94:97]
	v_mfma_f32_16x16x32_bf16 v[90:93], v[208:211], v[158:161], v[90:93]
	v_mfma_f32_16x16x32_bf16 v[86:89], v[200:203], v[166:169], v[86:89]
	v_mfma_f32_16x16x32_bf16 v[82:85], v[208:211], v[166:169], v[82:85]
	v_mfma_f32_16x16x32_bf16 v[78:81], v[200:203], v[180:183], v[78:81]
	v_mfma_f32_16x16x32_bf16 v[74:77], v[208:211], v[180:183], v[74:77]
	v_mfma_f32_16x16x32_bf16 v[70:73], v[200:203], v[192:195], v[70:73]
	v_mfma_f32_16x16x32_bf16 v[66:69], v[208:211], v[192:195], v[66:69]
	v_mfma_f32_16x16x32_bf16 v[94:97], v[204:207], v[162:165], v[94:97]
	v_mfma_f32_16x16x32_bf16 v[90:93], v[212:215], v[162:165], v[90:93]
	v_mfma_f32_16x16x32_bf16 v[86:89], v[204:207], v[176:179], v[86:89]
	v_mfma_f32_16x16x32_bf16 v[82:85], v[212:215], v[176:179], v[82:85]
	v_mfma_f32_16x16x32_bf16 v[78:81], v[204:207], v[184:187], v[78:81]
	v_mfma_f32_16x16x32_bf16 v[74:77], v[212:215], v[184:187], v[74:77]
	v_mfma_f32_16x16x32_bf16 v[70:73], v[204:207], v[196:199], v[70:73]
	v_mfma_f32_16x16x32_bf16 v[66:69], v[212:215], v[196:199], v[66:69]
	s_setprio 0
	s_mov_b32 m0, s52
	s_barrier
	ds_read_b128 v[158:161], v174 offset:16384
	ds_read_b128 v[162:165], v174 offset:17408
	ds_read_b128 v[166:169], v174 offset:18432
	ds_read_b128 v[176:179], v174 offset:19456
	ds_read_b128 v[180:183], v174 offset:20480
	ds_read_b128 v[184:187], v174 offset:21504
	ds_read_b128 v[192:195], v174 offset:22528
	ds_read_b128 v[196:199], v174 offset:23552
	global_load_lds_dwordx4 v146, s[48:49]
	s_mov_b32 m0, s53
	s_nop 0
	global_load_lds_dwordx4 v150, s[48:49]
	s_waitcnt vmcnt(10)
	s_barrier
	s_waitcnt lgkmcnt(0)
	s_setprio 1
	s_waitcnt lgkmcnt(0)
	v_mfma_f32_16x16x32_bf16 v[62:65], v[232:235], v[158:161], v[62:65]
	v_mfma_f32_16x16x32_bf16 v[58:61], v[240:243], v[158:161], v[58:61]
	v_mfma_f32_16x16x32_bf16 v[54:57], v[232:235], v[166:169], v[54:57]
	v_mfma_f32_16x16x32_bf16 v[50:53], v[240:243], v[166:169], v[50:53]
	v_mfma_f32_16x16x32_bf16 v[46:49], v[232:235], v[180:183], v[46:49]
	v_mfma_f32_16x16x32_bf16 v[42:45], v[240:243], v[180:183], v[42:45]
	v_mfma_f32_16x16x32_bf16 v[38:41], v[232:235], v[192:195], v[38:41]
	v_mfma_f32_16x16x32_bf16 v[34:37], v[240:243], v[192:195], v[34:37]
	v_mfma_f32_16x16x32_bf16 v[62:65], v[236:239], v[162:165], v[62:65]
	v_mfma_f32_16x16x32_bf16 v[58:61], v[244:247], v[162:165], v[58:61]
	v_mfma_f32_16x16x32_bf16 v[54:57], v[236:239], v[176:179], v[54:57]
	v_mfma_f32_16x16x32_bf16 v[50:53], v[244:247], v[176:179], v[50:53]
	v_mfma_f32_16x16x32_bf16 v[46:49], v[236:239], v[184:187], v[46:49]
	v_mfma_f32_16x16x32_bf16 v[42:45], v[244:247], v[184:187], v[42:45]
	v_mfma_f32_16x16x32_bf16 v[38:41], v[236:239], v[196:199], v[38:41]
	v_mfma_f32_16x16x32_bf16 v[34:37], v[244:247], v[196:199], v[34:37]
	s_setprio 0
	s_barrier
; #define G_STAGE(bufoff, gbase, voff) do { _Pragma("unroll") for (int _i = 0; _i < 2; ++_i) \
;         __builtin_amdgcn_global_load_lds((const unsigned*)((const char*)(gbase) + (voff)[_i]), (LAS unsigned*)(lds + (bufoff) + ldsw + _i * 8192), 16, 0, 0); } while (0)
; #define G_WAIT_V(n) asm volatile("s_waitcnt vmcnt(" #n ")" ::: "memory")
; #define G_WAIT_L(n) asm volatile("s_waitcnt lgkmcnt(" #n ")" ::: "memory")
; #define G_BAR __builtin_amdgcn_s_barrier()
; #define G_SCHED __builtin_amdgcn_sched_barrier(0)
; template <int MODE  , class Epi, class Sched>
; __device__ __forceinline__ void gemm_phase(LAS unsigned char* lds, const GemmDesc g, const Sched& S, const Epi& E) {
;     ...
;             G_WAIT_V(6); G_BAR; G_MMA(1, 1, At, B1); G_BAR;
;             G_LDB(B0, 1, 0); G_SCHED; G_LDA(At, 1, 0); G_STAGE(G_SA(0, 1), a2 + hstepA, voffA);
;             G_WAIT_L(8); G_BAR; G_WAIT_L(0); G_MMA(0, 0, At, B0); G_BAR; G_SCHED;
;             G_LDB(B1, 1, 1); G_STAGE(G_SB(1, 0), b3, voffB);
;             G_BAR; G_WAIT_L(0); G_MMA(0, 1, At, B1); G_BAR;
	v_add_u32_e32 v142, 0x18000, v172
	ds_read_b128 v[130:133], v142
	ds_read_b128 v[134:137], v142 offset:1024
	ds_read_b128 v[138:141], v142 offset:2048
	ds_read_b128 v[142:145], v142 offset:3072
	s_add_u32 s0, s46, 0x84000
	s_addc_u32 s1, s47, 0
	s_add_i32 s10, s59, s51
	s_mov_b32 m0, s10
	s_nop 0
	global_load_lds_dwordx4 v148, s[0:1]
	s_add_i32 m0, s10, 0x2000
	s_nop 0
	global_load_lds_dwordx4 v152, s[0:1]
	s_waitcnt vmcnt(6)
	s_barrier
	s_setprio 1
	v_mfma_f32_16x16x32_bf16 v[30:33], v[200:203], v[158:161], v[30:33]
	v_mfma_f32_16x16x32_bf16 v[26:29], v[208:211], v[158:161], v[26:29]
	v_mfma_f32_16x16x32_bf16 v[22:25], v[200:203], v[166:169], v[22:25]
	v_mfma_f32_16x16x32_bf16 v[18:21], v[208:211], v[166:169], v[18:21]
	v_mfma_f32_16x16x32_bf16 v[14:17], v[200:203], v[180:183], v[14:17]
	v_mfma_f32_16x16x32_bf16 v[10:13], v[208:211], v[180:183], v[10:13]
	v_mfma_f32_16x16x32_bf16 v[6:9], v[200:203], v[192:195], v[6:9]
	v_mfma_f32_16x16x32_bf16 v[2:5], v[208:211], v[192:195], v[2:5]
	v_mfma_f32_16x16x32_bf16 v[30:33], v[204:207], v[162:165], v[30:33]
	v_mfma_f32_16x16x32_bf16 v[26:29], v[212:215], v[162:165], v[26:29]
	v_mfma_f32_16x16x32_bf16 v[22:25], v[204:207], v[176:179], v[22:25]
	v_mfma_f32_16x16x32_bf16 v[18:21], v[212:215], v[176:179], v[18:21]
	v_mfma_f32_16x16x32_bf16 v[14:17], v[204:207], v[184:187], v[14:17]
	v_mfma_f32_16x16x32_bf16 v[10:13], v[212:215], v[184:187], v[10:13]
	v_mfma_f32_16x16x32_bf16 v[6:9], v[204:207], v[196:199], v[6:9]
	v_mfma_f32_16x16x32_bf16 v[2:5], v[212:215], v[196:199], v[2:5]
	s_setprio 0
	s_add_i32 s10, 0, 0x18000
	s_barrier
	s_add_u32 s0, s48, 0x84000
	s_addc_u32 s1, s49, 0
	s_mov_b32 m0, s54
	ds_read_b128 v[158:161], v174 offset:32768
	ds_read_b128 v[162:165], v174 offset:33792
	ds_read_b128 v[166:169], v174 offset:34816
	ds_read_b128 v[176:179], v174 offset:35840
	ds_read_b128 v[180:183], v174 offset:36864
	ds_read_b128 v[184:187], v174 offset:37888
	ds_read_b128 v[192:195], v174 offset:38912
	ds_read_b128 v[196:199], v174 offset:39936
	global_load_lds_dwordx4 v146, s[0:1]
	s_mov_b32 m0, s55
	s_nop 0
	global_load_lds_dwordx4 v150, s[0:1]
	s_waitcnt lgkmcnt(8)
	s_barrier
	s_waitcnt lgkmcnt(0)
	s_setprio 1
	s_waitcnt lgkmcnt(0)
	v_mfma_f32_16x16x32_bf16 v[126:129], v[130:133], v[158:161], v[126:129]
	v_mfma_f32_16x16x32_bf16 v[122:125], v[138:141], v[158:161], v[122:125]
	v_mfma_f32_16x16x32_bf16 v[118:121], v[130:133], v[166:169], v[118:121]
	v_mfma_f32_16x16x32_bf16 v[114:117], v[138:141], v[166:169], v[114:117]
	v_mfma_f32_16x16x32_bf16 v[110:113], v[130:133], v[180:183], v[110:113]
	v_mfma_f32_16x16x32_bf16 v[106:109], v[138:141], v[180:183], v[106:109]
	v_mfma_f32_16x16x32_bf16 v[102:105], v[130:133], v[192:195], v[102:105]
	v_mfma_f32_16x16x32_bf16 v[98:101], v[138:141], v[192:195], v[98:101]
	v_mfma_f32_16x16x32_bf16 v[126:129], v[134:137], v[162:165], v[126:129]
	v_mfma_f32_16x16x32_bf16 v[122:125], v[142:145], v[162:165], v[122:125]
	v_mfma_f32_16x16x32_bf16 v[118:121], v[134:137], v[176:179], v[118:121]
	v_mfma_f32_16x16x32_bf16 v[114:117], v[142:145], v[176:179], v[114:117]
	v_mfma_f32_16x16x32_bf16 v[110:113], v[134:137], v[184:187], v[110:113]
	v_mfma_f32_16x16x32_bf16 v[106:109], v[142:145], v[184:187], v[106:109]
	v_mfma_f32_16x16x32_bf16 v[102:105], v[134:137], v[196:199], v[102:105]
	v_mfma_f32_16x16x32_bf16 v[98:101], v[142:145], v[196:199], v[98:101]
	s_setprio 0
	s_barrier
	s_add_i32 s11, 0, 0x1c000
	s_add_i32 s0, s10, s51
	v_add_u32_e32 v175, s11, v172
	s_add_u32 s98, s46, 0x80
	s_addc_u32 s99, s47, 0
	s_mov_b32 m0, s0
	ds_read_b128 v[200:203], v175
	ds_read_b128 v[204:207], v175 offset:1024
	ds_read_b128 v[208:211], v175 offset:2048
	ds_read_b128 v[212:215], v175 offset:3072
	global_load_lds_dwordx4 v148, s[98:99]
	s_add_i32 m0, s0, 0x2000
	s_nop 0
	global_load_lds_dwordx4 v152, s[98:99]
	s_barrier
; #define G_STAGE(bufoff, gbase, voff) do { _Pragma("unroll") for (int _i = 0; _i < 2; ++_i) \
;         __builtin_amdgcn_global_load_lds((const unsigned*)((const char*)(gbase) + (voff)[_i]), (LAS unsigned*)(lds + (bufoff) + ldsw + _i * 8192), 16, 0, 0); } while (0)
; #define G_WAIT_V(n) asm volatile("s_waitcnt vmcnt(" #n ")" ::: "memory")
; #define G_WAIT_L(n) asm volatile("s_waitcnt lgkmcnt(" #n ")" ::: "memory")
; #define G_BAR __builtin_amdgcn_s_barrier()
; #define G_SCHED __builtin_amdgcn_sched_barrier(0)
; template <int MODE  , class Epi, class Sched>
; __device__ __forceinline__ void gemm_phase(LAS unsigned char* lds, const GemmDesc g, const Sched& S, const Epi& E) {
;     ...
;             G_LDB(B1, 1, 1); G_STAGE(G_SB(1, 0), b3, voffB);
;             G_BAR; G_WAIT_L(0); G_MMA(0, 1, At, B1); G_BAR;
;             G_LDA(At, 1, 1); G_STAGE(G_SA(1, 0), a3, voffA);
;             G_BAR; G_WAIT_L(0); G_MMA(1, 0, At, B0); G_BAR; G_SCHED;
;             G_STAGE(G_SB(1, 1), b3 + hstepB, voffB);
;             G_WAIT_V(6); G_BAR; G_MMA(1, 1, At, B1); G_BAR;
;         }
	s_waitcnt lgkmcnt(0)
	s_setprio 1
	s_waitcnt lgkmcnt(0)
	v_mfma_f32_16x16x32_bf16 v[94:97], v[200:203], v[158:161], v[94:97]
	v_mfma_f32_16x16x32_bf16 v[90:93], v[208:211], v[158:161], v[90:93]
	v_mfma_f32_16x16x32_bf16 v[86:89], v[200:203], v[166:169], v[86:89]
	v_mfma_f32_16x16x32_bf16 v[82:85], v[208:211], v[166:169], v[82:85]
	v_mfma_f32_16x16x32_bf16 v[78:81], v[200:203], v[180:183], v[78:81]
	v_mfma_f32_16x16x32_bf16 v[74:77], v[208:211], v[180:183], v[74:77]
	v_mfma_f32_16x16x32_bf16 v[70:73], v[200:203], v[192:195], v[70:73]
	v_mfma_f32_16x16x32_bf16 v[66:69], v[208:211], v[192:195], v[66:69]
	v_mfma_f32_16x16x32_bf16 v[94:97], v[204:207], v[162:165], v[94:97]
	v_mfma_f32_16x16x32_bf16 v[90:93], v[212:215], v[162:165], v[90:93]
	v_mfma_f32_16x16x32_bf16 v[86:89], v[204:207], v[176:179], v[86:89]
	v_mfma_f32_16x16x32_bf16 v[82:85], v[212:215], v[176:179], v[82:85]
	v_mfma_f32_16x16x32_bf16 v[78:81], v[204:207], v[184:187], v[78:81]
	v_mfma_f32_16x16x32_bf16 v[74:77], v[212:215], v[184:187], v[74:77]
	v_mfma_f32_16x16x32_bf16 v[70:73], v[204:207], v[196:199], v[70:73]
	v_mfma_f32_16x16x32_bf16 v[66:69], v[212:215], v[196:199], v[66:69]
	s_setprio 0
	s_mov_b32 m0, s56
	s_add_u32 s98, s48, 0x80
	s_addc_u32 s99, s49, 0
	s_barrier
	ds_read_b128 v[158:161], v174 offset:49152
	ds_read_b128 v[162:165], v174 offset:50176
	ds_read_b128 v[166:169], v174 offset:51200
	ds_read_b128 v[176:179], v174 offset:52224
	ds_read_b128 v[180:183], v174 offset:53248
	ds_read_b128 v[184:187], v174 offset:54272
	ds_read_b128 v[192:195], v174 offset:55296
	ds_read_b128 v[196:199], v174 offset:56320
	global_load_lds_dwordx4 v146, s[98:99]
	s_mov_b32 m0, s57
	s_nop 0
	global_load_lds_dwordx4 v150, s[98:99]
	s_waitcnt vmcnt(10)
	s_barrier
	s_waitcnt lgkmcnt(0)
	s_setprio 1
	s_waitcnt lgkmcnt(0)
	v_mfma_f32_16x16x32_bf16 v[62:65], v[130:133], v[158:161], v[62:65]
	v_mfma_f32_16x16x32_bf16 v[58:61], v[138:141], v[158:161], v[58:61]
	v_mfma_f32_16x16x32_bf16 v[54:57], v[130:133], v[166:169], v[54:57]
	v_mfma_f32_16x16x32_bf16 v[50:53], v[138:141], v[166:169], v[50:53]
	v_mfma_f32_16x16x32_bf16 v[46:49], v[130:133], v[180:183], v[46:49]
	v_mfma_f32_16x16x32_bf16 v[42:45], v[138:141], v[180:183], v[42:45]
	v_mfma_f32_16x16x32_bf16 v[38:41], v[130:133], v[192:195], v[38:41]
	v_mfma_f32_16x16x32_bf16 v[34:37], v[138:141], v[192:195], v[34:37]
	v_mfma_f32_16x16x32_bf16 v[62:65], v[134:137], v[162:165], v[62:65]
	v_mfma_f32_16x16x32_bf16 v[58:61], v[142:145], v[162:165], v[58:61]
	v_mfma_f32_16x16x32_bf16 v[54:57], v[134:137], v[176:179], v[54:57]
	v_mfma_f32_16x16x32_bf16 v[50:53], v[142:145], v[176:179], v[50:53]
	v_mfma_f32_16x16x32_bf16 v[46:49], v[134:137], v[184:187], v[46:49]
	v_mfma_f32_16x16x32_bf16 v[42:45], v[142:145], v[184:187], v[42:45]
	v_mfma_f32_16x16x32_bf16 v[38:41], v[134:137], v[196:199], v[38:41]
	v_mfma_f32_16x16x32_bf16 v[34:37], v[142:145], v[196:199], v[34:37]
	s_setprio 0
	s_barrier
	v_add_u32_e32 v244, s58, v172
	ds_read_b128 v[232:235], v244
	ds_read_b128 v[236:239], v244 offset:1024
	ds_read_b128 v[240:243], v244 offset:2048
	ds_read_b128 v[244:247], v244 offset:3072
	s_add_u32 s0, s46, 0x84080
	s_addc_u32 s1, s47, 0
	s_add_i32 s10, s11, s51
	s_mov_b32 m0, s10
	s_nop 0
	global_load_lds_dwordx4 v148, s[0:1]
	s_add_i32 m0, s10, 0x2000
	s_nop 0
	global_load_lds_dwordx4 v152, s[0:1]
	s_waitcnt vmcnt(6)
	s_barrier
	s_setprio 1
	v_mfma_f32_16x16x32_bf16 v[30:33], v[200:203], v[158:161], v[30:33]
	s_add_i32 s68, s68, 2
	s_add_u32 s21, s21, 0x100
	s_addc_u32 s67, s67, 0
	s_cmp_gt_u32 s68, 13
	s_mov_b64 s[42:43], s[44:45]
	v_mfma_f32_16x16x32_bf16 v[26:29], v[208:211], v[158:161], v[26:29]
	v_mfma_f32_16x16x32_bf16 v[22:25], v[200:203], v[166:169], v[22:25]
	v_mfma_f32_16x16x32_bf16 v[18:21], v[208:211], v[166:169], v[18:21]
	v_mfma_f32_16x16x32_bf16 v[14:17], v[200:203], v[180:183], v[14:17]
	v_mfma_f32_16x16x32_bf16 v[10:13], v[208:211], v[180:183], v[10:13]
	v_mfma_f32_16x16x32_bf16 v[6:9], v[200:203], v[192:195], v[6:9]
	v_mfma_f32_16x16x32_bf16 v[2:5], v[208:211], v[192:195], v[2:5]
	v_mfma_f32_16x16x32_bf16 v[30:33], v[204:207], v[162:165], v[30:33]
	v_mfma_f32_16x16x32_bf16 v[26:29], v[212:215], v[162:165], v[26:29]
	v_mfma_f32_16x16x32_bf16 v[22:25], v[204:207], v[176:179], v[22:25]
	v_mfma_f32_16x16x32_bf16 v[18:21], v[212:215], v[176:179], v[18:21]
	v_mfma_f32_16x16x32_bf16 v[14:17], v[204:207], v[184:187], v[14:17]
	v_mfma_f32_16x16x32_bf16 v[10:13], v[212:215], v[184:187], v[10:13]
	v_mfma_f32_16x16x32_bf16 v[6:9], v[204:207], v[196:199], v[6:9]
	v_mfma_f32_16x16x32_bf16 v[2:5], v[212:215], v[196:199], v[2:5]
	s_setprio 0
	s_cbranch_scc1 .Lkdone_sa
	s_barrier
	s_branch .LBB0_815

; __device__ __forceinline__ float bf_lo(unsigned w) { return __uint_as_float(w << 16); }
; __device__ __forceinline__ float bf_hi(unsigned w) { return __uint_as_float(w & 0xffff0000u); }
;     __device__ __forceinline__ bool operator()(f32x4 (&acc)[2][2][4][2], const Unit& u, int wr, int wc, int fr, int fq) const {
;         const int r0 = u.pm * BM + wr * 64 + fr, c0 = u.pn * BM + wc * 32 + fq * 8;
;         const bf16_t* S = u.kh ? SGB : SGR;
; #pragma unroll
;         for (int ai = 0; ai < 2; ++ai)
; #pragma unroll
;             for (int m = 0; m < 4; ++m) { const size_t off = (size_t)(r0 + ai * HALF + m * 16) * D + c0;
; #pragma unroll
;                 for (int bj = 0; bj < 2; ++bj) { const u32x4 s = *(const u32x4*)(S + off + bj * HALF);
;                     f32x4 v0 = acc[ai][bj][m][0], v1 = acc[ai][bj][m][1];
;                     v0[0] *= bf_lo(s.x); v0[1] *= bf_hi(s.x); v0[2] *= bf_lo(s.y); v0[3] *= bf_hi(s.y);
;                     v1[0] *= bf_lo(s.z); v1[1] *= bf_hi(s.z); v1[2] *= bf_lo(s.w); v1[3] *= bf_hi(s.w);
;                     acc[ai][bj][m][0] = v0; acc[ai][bj][m][1] = v1; } }
.Lkepi_sa:
	s_waitcnt lgkmcnt(0)
	s_cmp_lg_u32 s65, 0
	s_cselect_b64 s[42:43], -1, 0
	s_cmp_eq_u32 s65, 0
	s_cselect_b64 s[0:1], -1, 0
	s_and_b64 vcc, s[0:1], exec
	v_lshl_add_u32 v160, s64, 8, v1
	v_lshl_or_b32 v158, s66, 8, v173
	s_cselect_b32 s0, s5, s15
	s_cselect_b32 s1, s4, s14
	v_mov_b32_e32 v130, s1
	v_mov_b32_e32 v131, s0
	v_ashrrev_i32_e32 v159, 31, v158
	v_ashrrev_i32_e32 v161, 31, v160
	v_lshl_add_u64 v[170:171], v[158:159], 1, v[130:131]
	v_lshlrev_b64 v[130:131], 12, v[160:161]
	v_or_b32_e32 v162, 16, v160
	v_lshl_add_u64 v[130:131], v[170:171], 0, v[130:131]
	v_ashrrev_i32_e32 v163, 31, v162
	v_mov_b64_e32 v[228:229], v[130:131]
	global_load_dwordx4 v[142:145], v[130:131], off
	global_load_dwordx4 v[176:179], v[130:131], off offset:256
	v_lshlrev_b64 v[130:131], 12, v[162:163]
	v_or_b32_e32 v164, 32, v160
	v_lshl_add_u64 v[130:131], v[170:171], 0, v[130:131]
	v_ashrrev_i32_e32 v165, 31, v164
	global_load_dwordx4 v[180:183], v[130:131], off
	global_load_dwordx4 v[184:187], v[130:131], off offset:256
	v_lshlrev_b64 v[130:131], 12, v[164:165]
	v_lshl_add_u64 v[130:131], v[170:171], 0, v[130:131]
	global_load_dwordx4 v[192:195], v[130:131], off
	global_load_dwordx4 v[196:199], v[130:131], off offset:256
	v_or_b32_e32 v166, 48, v160
	v_add_u32_e32 v168, 0x80, v160
	v_ashrrev_i32_e32 v167, 31, v166
	v_ashrrev_i32_e32 v169, 31, v168
	v_lshlrev_b64 v[130:131], 12, v[166:167]
	v_lshlrev_b64 v[132:133], 12, v[168:169]
	v_lshl_add_u64 v[130:131], v[170:171], 0, v[130:131]
	v_lshl_add_u64 v[134:135], v[170:171], 0, v[132:133]
	global_load_dwordx4 v[200:203], v[130:131], off
	global_load_dwordx4 v[138:141], v[130:131], off offset:256
	s_nop 0
	global_load_dwordx4 v[130:133], v[134:135], off
	s_nop 0
	global_load_dwordx4 v[134:137], v[134:135], off offset:256
	s_mov_b64 s[0:1], 0x90000
	v_lshl_add_u64 v[226:227], v[228:229], 0, s[0:1]
	global_load_dwordx4 v[232:235], v[226:227], off
	global_load_dwordx4 v[236:239], v[226:227], off offset:256
	s_mov_b64 s[0:1], 0xa0000
	v_lshl_add_u64 v[226:227], v[228:229], 0, s[0:1]
	global_load_dwordx4 v[240:243], v[226:227], off
	global_load_dwordx4 v[244:247], v[226:227], off offset:256
	s_mov_b64 s[0:1], 0xb0000
	v_lshl_add_u64 v[226:227], v[228:229], 0, s[0:1]
	global_load_dwordx4 v[248:251], v[226:227], off
	global_load_dwordx4 v[252:255], v[226:227], off offset:256
	s_waitcnt vmcnt(0)
	v_lshlrev_b32_e32 v188, 16, v142
	v_and_b32_e32 v189, 0xffff0000, v142
	v_lshlrev_b32_e32 v142, 16, v143
	v_and_b32_e32 v143, 0xffff0000, v143
	v_pk_mul_f32 v[128:129], v[128:129], v[142:143]
	v_lshlrev_b32_e32 v204, 16, v144
	v_and_b32_e32 v205, 0xffff0000, v144
	v_lshlrev_b32_e32 v144, 16, v145
	v_lshlrev_b32_e32 v142, 16, v192
	v_and_b32_e32 v143, 0xffff0000, v192
	v_pk_mul_f32 v[110:111], v[110:111], v[142:143]
	v_lshlrev_b32_e32 v142, 16, v193
	v_and_b32_e32 v143, 0xffff0000, v193
	v_pk_mul_f32 v[112:113], v[112:113], v[142:143]
	v_add_u32_e32 v142, 0x90, v160
	v_and_b32_e32 v145, 0xffff0000, v145
	v_ashrrev_i32_e32 v143, 31, v142
	v_lshlrev_b32_e32 v210, 16, v180
	v_and_b32_e32 v211, 0xffff0000, v180
	v_lshlrev_b32_e32 v180, 16, v181
	v_and_b32_e32 v181, 0xffff0000, v181
	v_pk_mul_f32 v[124:125], v[124:125], v[144:145]
	v_lshlrev_b64 v[144:145], 12, v[142:143]
	v_lshlrev_b32_e32 v206, 16, v176
	v_and_b32_e32 v207, 0xffff0000, v176
	v_lshlrev_b32_e32 v176, 16, v177
	v_and_b32_e32 v177, 0xffff0000, v177
	v_lshlrev_b32_e32 v208, 16, v178
	v_and_b32_e32 v209, 0xffff0000, v178
	v_lshlrev_b32_e32 v178, 16, v179
	v_and_b32_e32 v179, 0xffff0000, v179
	v_pk_mul_f32 v[120:121], v[120:121], v[180:181]
	v_lshl_add_u64 v[144:145], v[170:171], 0, v[144:145]
	v_lshlrev_b32_e32 v180, 16, v194
	v_and_b32_e32 v181, 0xffff0000, v194
	v_pk_mul_f32 v[96:97], v[96:97], v[176:177]
	v_pk_mul_f32 v[92:93], v[92:93], v[178:179]
	v_mov_b64_e32 v[176:177], v[232:233]
	v_mov_b64_e32 v[178:179], v[234:235]
	v_pk_mul_f32 v[106:107], v[106:107], v[180:181]
	v_lshlrev_b32_e32 v180, 16, v195
	v_and_b32_e32 v181, 0xffff0000, v195
	v_lshlrev_b32_e32 v212, 16, v182
	v_and_b32_e32 v213, 0xffff0000, v182
	v_lshlrev_b32_e32 v182, 16, v183
	v_and_b32_e32 v183, 0xffff0000, v183
	v_pk_mul_f32 v[108:109], v[108:109], v[180:181]
	v_lshlrev_b32_e32 v180, 16, v196
	v_and_b32_e32 v181, 0xffff0000, v196
	v_pk_mul_f32 v[116:117], v[116:117], v[182:183]
	v_pk_mul_f32 v[78:79], v[78:79], v[180:181]
	v_mov_b64_e32 v[180:181], v[236:237]
	v_mov_b64_e32 v[182:183], v[238:239]
	v_lshlrev_b32_e32 v144, 16, v198
	v_and_b32_e32 v145, 0xffff0000, v198
	v_pk_mul_f32 v[74:75], v[74:75], v[144:145]
	v_lshlrev_b32_e32 v144, 16, v199
	v_and_b32_e32 v145, 0xffff0000, v199
	v_lshlrev_b32_e32 v214, 16, v184
	v_and_b32_e32 v215, 0xffff0000, v184
	v_lshlrev_b32_e32 v184, 16, v185
	v_and_b32_e32 v185, 0xffff0000, v185
	v_pk_mul_f32 v[76:77], v[76:77], v[144:145]
	v_add_u32_e32 v144, 0xa0, v160
	v_pk_mul_f32 v[88:89], v[88:89], v[184:185]
	v_lshlrev_b32_e32 v184, 16, v197
	v_and_b32_e32 v185, 0xffff0000, v197
	v_ashrrev_i32_e32 v145, 31, v144
	v_pk_mul_f32 v[80:81], v[80:81], v[184:185]
	v_lshlrev_b64 v[184:185], 12, v[144:145]
	v_lshlrev_b32_e32 v216, 16, v186
	v_and_b32_e32 v217, 0xffff0000, v186
	v_lshlrev_b32_e32 v186, 16, v187
	v_and_b32_e32 v187, 0xffff0000, v187
	v_pk_mul_f32 v[126:127], v[126:127], v[188:189]
	v_lshl_add_u64 v[188:189], v[170:171], 0, v[184:185]
	v_pk_mul_f32 v[84:85], v[84:85], v[186:187]
	v_mov_b64_e32 v[184:185], v[240:241]
	v_mov_b64_e32 v[186:187], v[242:243]
	v_lshlrev_b32_e32 v192, 16, v200
	v_and_b32_e32 v193, 0xffff0000, v200
	v_pk_mul_f32 v[102:103], v[102:103], v[192:193]
	v_lshlrev_b32_e32 v192, 16, v201
	v_and_b32_e32 v193, 0xffff0000, v201
; __device__ __forceinline__ float bf_lo(unsigned w) { return __uint_as_float(w << 16); }
; __device__ __forceinline__ float bf_hi(unsigned w) { return __uint_as_float(w & 0xffff0000u); }
;     __device__ __forceinline__ bool operator()(f32x4 (&acc)[2][2][4][2], const Unit& u, int wr, int wc, int fr, int fq) const {
;     ...
;                 for (int bj = 0; bj < 2; ++bj) { const u32x4 s = *(const u32x4*)(S + off + bj * HALF);
;                     f32x4 v0 = acc[ai][bj][m][0], v1 = acc[ai][bj][m][1];
;                     v0[0] *= bf_lo(s.x); v0[1] *= bf_hi(s.x); v0[2] *= bf_lo(s.y); v0[3] *= bf_hi(s.y);
;                     v1[0] *= bf_lo(s.z); v1[1] *= bf_hi(s.z); v1[2] *= bf_lo(s.w); v1[3] *= bf_hi(s.w);
;                     acc[ai][bj][m][0] = v0; acc[ai][bj][m][1] = v1; } }
;         if (u.kh == 0) return false;
	v_pk_mul_f32 v[104:105], v[104:105], v[192:193]
	v_lshlrev_b32_e32 v192, 16, v202
	v_and_b32_e32 v193, 0xffff0000, v202
	v_pk_mul_f32 v[98:99], v[98:99], v[192:193]
	v_mov_b64_e32 v[192:193], v[244:245]
	v_mov_b64_e32 v[194:195], v[246:247]
	v_lshlrev_b32_e32 v188, 16, v138
	v_and_b32_e32 v189, 0xffff0000, v138
	v_lshlrev_b32_e32 v138, 16, v139
	v_and_b32_e32 v139, 0xffff0000, v139
	v_pk_mul_f32 v[72:73], v[72:73], v[138:139]
	v_add_u32_e32 v138, 0xb0, v160
	v_ashrrev_i32_e32 v139, 31, v138
	v_pk_mul_f32 v[70:71], v[70:71], v[188:189]
	v_lshlrev_b64 v[188:189], 12, v[138:139]
	v_lshlrev_b32_e32 v196, 16, v203
	v_and_b32_e32 v197, 0xffff0000, v203
	v_lshl_add_u64 v[170:171], v[170:171], 0, v[188:189]
	v_pk_mul_f32 v[100:101], v[100:101], v[196:197]
	v_mov_b64_e32 v[196:197], v[248:249]
	v_mov_b64_e32 v[198:199], v[250:251]
	v_mov_b64_e32 v[200:201], v[252:253]
	v_mov_b64_e32 v[202:203], v[254:255]
	v_lshlrev_b32_e32 v188, 16, v140
	v_and_b32_e32 v189, 0xffff0000, v140
	v_lshlrev_b32_e32 v140, 16, v141
	v_and_b32_e32 v141, 0xffff0000, v141
	v_pk_mul_f32 v[68:69], v[68:69], v[140:141]
	v_lshlrev_b32_e32 v140, 16, v130
	v_and_b32_e32 v141, 0xffff0000, v130
	v_lshlrev_b32_e32 v130, 16, v131
	v_and_b32_e32 v131, 0xffff0000, v131
	v_pk_mul_f32 v[64:65], v[64:65], v[130:131]
	v_lshlrev_b32_e32 v130, 16, v132
	v_and_b32_e32 v131, 0xffff0000, v132
	v_pk_mul_f32 v[58:59], v[58:59], v[130:131]
	v_lshlrev_b32_e32 v130, 16, v133
	v_and_b32_e32 v131, 0xffff0000, v133
	v_pk_mul_f32 v[60:61], v[60:61], v[130:131]
	v_lshlrev_b32_e32 v130, 16, v134
	v_and_b32_e32 v131, 0xffff0000, v134
	v_pk_mul_f32 v[30:31], v[30:31], v[130:131]
	v_lshlrev_b32_e32 v130, 16, v135
	v_and_b32_e32 v131, 0xffff0000, v135
	v_pk_mul_f32 v[32:33], v[32:33], v[130:131]
	v_lshlrev_b32_e32 v130, 16, v136
	v_and_b32_e32 v131, 0xffff0000, v136
	v_pk_mul_f32 v[26:27], v[26:27], v[130:131]
	v_lshlrev_b32_e32 v130, 16, v137
	v_and_b32_e32 v131, 0xffff0000, v137
	v_pk_mul_f32 v[28:29], v[28:29], v[130:131]
	s_waitcnt vmcnt(0)
	v_lshlrev_b32_e32 v130, 16, v176
	v_and_b32_e32 v131, 0xffff0000, v176
	v_pk_mul_f32 v[54:55], v[54:55], v[130:131]
	v_lshlrev_b32_e32 v130, 16, v177
	v_and_b32_e32 v131, 0xffff0000, v177
	v_pk_mul_f32 v[56:57], v[56:57], v[130:131]
	v_lshlrev_b32_e32 v130, 16, v178
	v_and_b32_e32 v131, 0xffff0000, v178
	v_pk_mul_f32 v[50:51], v[50:51], v[130:131]
	v_lshlrev_b32_e32 v130, 16, v179
	v_and_b32_e32 v131, 0xffff0000, v179
	v_pk_mul_f32 v[52:53], v[52:53], v[130:131]
	v_lshlrev_b32_e32 v130, 16, v180
	v_and_b32_e32 v131, 0xffff0000, v180
	v_pk_mul_f32 v[22:23], v[22:23], v[130:131]
	v_lshlrev_b32_e32 v130, 16, v181
	v_and_b32_e32 v131, 0xffff0000, v181
	v_pk_mul_f32 v[24:25], v[24:25], v[130:131]
	v_lshlrev_b32_e32 v130, 16, v182
	v_and_b32_e32 v131, 0xffff0000, v182
	v_pk_mul_f32 v[18:19], v[18:19], v[130:131]
	v_lshlrev_b32_e32 v130, 16, v183
	v_and_b32_e32 v131, 0xffff0000, v183
	v_pk_mul_f32 v[20:21], v[20:21], v[130:131]
	v_pk_mul_f32 v[122:123], v[122:123], v[204:205]
	v_pk_mul_f32 v[94:95], v[94:95], v[206:207]
	v_lshlrev_b32_e32 v130, 16, v184
	v_and_b32_e32 v131, 0xffff0000, v184
	v_pk_mul_f32 v[46:47], v[46:47], v[130:131]
	v_lshlrev_b32_e32 v130, 16, v185
	v_and_b32_e32 v131, 0xffff0000, v185
	v_pk_mul_f32 v[48:49], v[48:49], v[130:131]
	v_lshlrev_b32_e32 v130, 16, v186
	v_and_b32_e32 v131, 0xffff0000, v186
	v_pk_mul_f32 v[42:43], v[42:43], v[130:131]
	v_lshlrev_b32_e32 v130, 16, v187
	v_and_b32_e32 v131, 0xffff0000, v187
	v_pk_mul_f32 v[44:45], v[44:45], v[130:131]
	v_lshlrev_b32_e32 v130, 16, v192
	v_and_b32_e32 v131, 0xffff0000, v192
	v_pk_mul_f32 v[14:15], v[14:15], v[130:131]
	v_lshlrev_b32_e32 v130, 16, v193
	v_and_b32_e32 v131, 0xffff0000, v193
	v_pk_mul_f32 v[16:17], v[16:17], v[130:131]
	v_lshlrev_b32_e32 v130, 16, v194
	v_and_b32_e32 v131, 0xffff0000, v194
	v_pk_mul_f32 v[10:11], v[10:11], v[130:131]
	v_lshlrev_b32_e32 v130, 16, v195
	v_and_b32_e32 v131, 0xffff0000, v195
	v_pk_mul_f32 v[12:13], v[12:13], v[130:131]
	v_lshlrev_b32_e32 v130, 16, v196
	v_and_b32_e32 v131, 0xffff0000, v196
	v_pk_mul_f32 v[38:39], v[38:39], v[130:131]
	v_lshlrev_b32_e32 v130, 16, v197
	v_and_b32_e32 v131, 0xffff0000, v197
	v_pk_mul_f32 v[40:41], v[40:41], v[130:131]
	v_lshlrev_b32_e32 v130, 16, v198
	v_and_b32_e32 v131, 0xffff0000, v198
	v_pk_mul_f32 v[34:35], v[34:35], v[130:131]
	v_lshlrev_b32_e32 v130, 16, v199
	v_and_b32_e32 v131, 0xffff0000, v199
	v_pk_mul_f32 v[36:37], v[36:37], v[130:131]
	v_lshlrev_b32_e32 v130, 16, v200
	v_and_b32_e32 v131, 0xffff0000, v200
	v_pk_mul_f32 v[6:7], v[6:7], v[130:131]
	v_lshlrev_b32_e32 v130, 16, v201
	v_and_b32_e32 v131, 0xffff0000, v201
	v_pk_mul_f32 v[8:9], v[8:9], v[130:131]
	v_lshlrev_b32_e32 v130, 16, v202
	v_and_b32_e32 v131, 0xffff0000, v202
	v_pk_mul_f32 v[2:3], v[2:3], v[130:131]
	v_lshlrev_b32_e32 v130, 16, v203
	v_and_b32_e32 v131, 0xffff0000, v203
	v_pk_mul_f32 v[90:91], v[90:91], v[208:209]
	v_pk_mul_f32 v[118:119], v[118:119], v[210:211]
	v_pk_mul_f32 v[114:115], v[114:115], v[212:213]
	v_pk_mul_f32 v[86:87], v[86:87], v[214:215]
	v_pk_mul_f32 v[82:83], v[82:83], v[216:217]
	v_pk_mul_f32 v[66:67], v[66:67], v[188:189]
	v_pk_mul_f32 v[62:63], v[62:63], v[140:141]
	v_pk_mul_f32 v[4:5], v[4:5], v[130:131]
	s_cbranch_vccnz .LBB0_818
; __device__ __forceinline__ unsigned pk_bf16(float lo, float hi) { const f32x2_t v = {lo, hi}; return __builtin_bit_cast(unsigned, __builtin_convertvector(v, bf16x2_t)); }
;     __device__ __forceinline__ bool operator()(f32x4 (&acc)[2][2][4][2], const Unit& u, int wr, int wc, int fr, int fq) const {
;     ...
; #pragma unroll
;         for (int ai = 0; ai < 2; ++ai)
; #pragma unroll
;             for (int m = 0; m < 4; ++m) { const size_t off = (size_t)(r0 + ai * HALF + m * 16) * LDP + c0;
; #pragma unroll
;                 for (int bj = 0; bj < 2; ++bj) { const f32x4 v0 = acc[ai][bj][m][0], v1 = acc[ai][bj][m][1];
;                     u32x4 w; w.x = pk_bf16(v0[0], v0[1]); w.y = pk_bf16(v0[2], v0[3]); w.z = pk_bf16(v1[0], v1[1]); w.w = pk_bf16(v1[2], v1[3]);
;                     *(u32x4*)(MG + off + bj * HALF) = w; } }
	v_mov_b64_e32 v[134:135], s[12:13]
	v_mad_i64_i32 v[136:137], s[0:1], v160, s60, v[134:135]
	v_lshlrev_b64 v[140:141], 1, v[158:159]
	v_cvt_pk_bf16_f32 v130, v126, v127
	v_cvt_pk_bf16_f32 v131, v128, v129
	v_cvt_pk_bf16_f32 v132, v122, v123
	v_cvt_pk_bf16_f32 v133, v124, v125
	v_lshl_add_u64 v[136:137], v[136:137], 0, v[140:141]
	global_store_dwordx4 v[136:137], v[130:133], off
	s_nop 1
	v_cvt_pk_bf16_f32 v130, v94, v95
	v_cvt_pk_bf16_f32 v131, v96, v97
	v_cvt_pk_bf16_f32 v132, v90, v91
	v_cvt_pk_bf16_f32 v133, v92, v93
	global_store_dwordx4 v[136:137], v[130:133], off offset:256
	v_mad_i64_i32 v[136:137], s[0:1], v162, s60, v[134:135]
	s_nop 0
	v_cvt_pk_bf16_f32 v130, v118, v119
	v_cvt_pk_bf16_f32 v131, v120, v121
	v_cvt_pk_bf16_f32 v132, v114, v115
	v_cvt_pk_bf16_f32 v133, v116, v117
	v_lshl_add_u64 v[136:137], v[136:137], 0, v[140:141]
	global_store_dwordx4 v[136:137], v[130:133], off
	s_nop 1
	v_cvt_pk_bf16_f32 v130, v86, v87
	v_cvt_pk_bf16_f32 v131, v88, v89
	v_cvt_pk_bf16_f32 v132, v82, v83
	v_cvt_pk_bf16_f32 v133, v84, v85
	global_store_dwordx4 v[136:137], v[130:133], off offset:256
	v_mad_i64_i32 v[136:137], s[0:1], v164, s60, v[134:135]
	s_nop 0
	v_cvt_pk_bf16_f32 v130, v110, v111
	v_cvt_pk_bf16_f32 v131, v112, v113
	v_cvt_pk_bf16_f32 v132, v106, v107
	v_cvt_pk_bf16_f32 v133, v108, v109
	v_lshl_add_u64 v[136:137], v[136:137], 0, v[140:141]
	global_store_dwordx4 v[136:137], v[130:133], off
	s_nop 1
	v_cvt_pk_bf16_f32 v130, v78, v79
	v_cvt_pk_bf16_f32 v131, v80, v81
	v_cvt_pk_bf16_f32 v132, v74, v75
	v_cvt_pk_bf16_f32 v133, v76, v77
	global_store_dwordx4 v[136:137], v[130:133], off offset:256
	v_mad_i64_i32 v[136:137], s[0:1], v166, s60, v[134:135]
	s_nop 0
	v_cvt_pk_bf16_f32 v130, v102, v103
	v_cvt_pk_bf16_f32 v131, v104, v105
	v_cvt_pk_bf16_f32 v132, v98, v99
	v_cvt_pk_bf16_f32 v133, v100, v101
	v_lshl_add_u64 v[136:137], v[136:137], 0, v[140:141]
	global_store_dwordx4 v[136:137], v[130:133], off
	s_nop 1
	v_cvt_pk_bf16_f32 v130, v70, v71
	v_cvt_pk_bf16_f32 v131, v72, v73
	v_cvt_pk_bf16_f32 v132, v66, v67
	v_cvt_pk_bf16_f32 v133, v68, v69
	global_store_dwordx4 v[136:137], v[130:133], off offset:256
	v_mad_i64_i32 v[136:137], s[0:1], v168, s60, v[134:135]
	s_nop 0
	v_cvt_pk_bf16_f32 v130, v62, v63
	v_cvt_pk_bf16_f32 v131, v64, v65
	v_cvt_pk_bf16_f32 v132, v58, v59
	v_cvt_pk_bf16_f32 v133, v60, v61
	v_lshl_add_u64 v[136:137], v[136:137], 0, v[140:141]
	global_store_dwordx4 v[136:137], v[130:133], off
	s_nop 1
	v_cvt_pk_bf16_f32 v130, v30, v31
	v_cvt_pk_bf16_f32 v131, v32, v33
	v_cvt_pk_bf16_f32 v132, v26, v27
	v_cvt_pk_bf16_f32 v133, v28, v29
	global_store_dwordx4 v[136:137], v[130:133], off offset:256
	v_mad_i64_i32 v[136:137], s[0:1], v142, s60, v[134:135]
	s_nop 0
	v_cvt_pk_bf16_f32 v130, v54, v55
	v_cvt_pk_bf16_f32 v131, v56, v57
	v_cvt_pk_bf16_f32 v132, v50, v51
	v_cvt_pk_bf16_f32 v133, v52, v53
	v_lshl_add_u64 v[136:137], v[136:137], 0, v[140:141]
	global_store_dwordx4 v[136:137], v[130:133], off
	s_nop 1
	v_cvt_pk_bf16_f32 v130, v22, v23
	v_cvt_pk_bf16_f32 v131, v24, v25
	v_cvt_pk_bf16_f32 v132, v18, v19
	v_cvt_pk_bf16_f32 v133, v20, v21
	global_store_dwordx4 v[136:137], v[130:133], off offset:256
	v_mad_i64_i32 v[136:137], s[0:1], v144, s60, v[134:135]
	s_nop 0
	v_cvt_pk_bf16_f32 v130, v46, v47
	v_cvt_pk_bf16_f32 v131, v48, v49
	v_cvt_pk_bf16_f32 v132, v42, v43
	v_cvt_pk_bf16_f32 v133, v44, v45
	v_lshl_add_u64 v[136:137], v[136:137], 0, v[140:141]
	global_store_dwordx4 v[136:137], v[130:133], off
	v_mad_i64_i32 v[134:135], s[0:1], v138, s60, v[134:135]
	s_nop 0
	v_cvt_pk_bf16_f32 v130, v14, v15
	v_cvt_pk_bf16_f32 v131, v16, v17
	v_cvt_pk_bf16_f32 v132, v10, v11
	v_cvt_pk_bf16_f32 v133, v12, v13
	global_store_dwordx4 v[136:137], v[130:133], off offset:256
	v_lshl_add_u64 v[134:135], v[134:135], 0, v[140:141]
	s_nop 0
	v_cvt_pk_bf16_f32 v130, v38, v39
	v_cvt_pk_bf16_f32 v131, v40, v41
	v_cvt_pk_bf16_f32 v132, v34, v35
	v_cvt_pk_bf16_f32 v133, v36, v37
	global_store_dwordx4 v[134:135], v[130:133], off
	s_nop 1
	v_cvt_pk_bf16_f32 v130, v6, v7
	v_cvt_pk_bf16_f32 v131, v8, v9
	v_cvt_pk_bf16_f32 v132, v2, v3
	v_cvt_pk_bf16_f32 v133, v4, v5
	global_store_dwordx4 v[134:135], v[130:133], off offset:256

; #define G_STAGE(bufoff, gbase, voff) do { _Pragma("unroll") for (int _i = 0; _i < 2; ++_i) \
;         __builtin_amdgcn_global_load_lds((const unsigned*)((const char*)(gbase) + (voff)[_i]), (LAS unsigned*)(lds + (bufoff) + ldsw + _i * 8192), 16, 0, 0); } while (0)
; #define G_WAIT_L(n) asm volatile("s_waitcnt lgkmcnt(" #n ")" ::: "memory")
; #define G_BAR __builtin_amdgcn_s_barrier()
; #define G_SCHED __builtin_amdgcn_sched_barrier(0)
; template <int MODE  , class Epi, class Sched>
; __device__ __forceinline__ void gemm_phase(LAS unsigned char* lds, const GemmDesc g, const Sched& S, const Epi& E) {
;     ...
;             G_LDB(B0, 0, 0); G_SCHED; G_LDA(At, 0, 0); G_STAGE(G_SA(1, 1), a1 + hstepA, voffA);
;             G_WAIT_L(8); G_BAR; G_WAIT_L(0); G_MMA(0, 0, At, B0); G_BAR; G_SCHED;
;             G_LDB(B1, 0, 1); G_STAGE(G_SB(0, 0), b2, voffB);
;             G_BAR; G_WAIT_L(0); G_MMA(0, 1, At, B1); G_BAR;
;             G_LDA(At, 0, 1); G_STAGE(G_SA(0, 0), a2, voffA);
;             G_BAR; G_WAIT_L(0); G_MMA(1, 0, At, B0); G_BAR; G_SCHED;
.Lnodb_sb:
	v_add_u32_e32 v244, s57, v174
	ds_read_b128 v[232:235], v244
	ds_read_b128 v[236:239], v244 offset:1024
	ds_read_b128 v[240:243], v244 offset:2048
	ds_read_b128 v[244:247], v244 offset:3072
.LBB0_897:
	s_add_u32 s42, s40, 0x100
	s_addc_u32 s43, s41, 0
	s_cmp_eq_u32 s71, 12
	s_cselect_b32 s47, s21, s43
	s_cselect_b32 s46, s20, s42
	s_cselect_b32 s45, s3, s70
	s_cselect_b32 s44, s2, s19
	s_add_u32 s98, s40, 0x84080
	s_addc_u32 s99, s41, 0
	s_add_i32 m0, s50, 0xc000
	ds_read_b128 v[158:161], v176
	ds_read_b128 v[162:165], v176 offset:1024
	ds_read_b128 v[166:169], v176 offset:2048
	ds_read_b128 v[170:173], v176 offset:3072
	ds_read_b128 v[178:181], v176 offset:4096
	ds_read_b128 v[182:185], v176 offset:5120
	ds_read_b128 v[186:189], v176 offset:6144
	ds_read_b128 v[192:195], v176 offset:7168
	global_load_lds_dwordx4 v146, s[98:99]
	s_add_i32 m0, s50, 0xe000
	s_nop 0
	global_load_lds_dwordx4 v150, s[98:99]
	s_waitcnt lgkmcnt(8)
	s_barrier
	s_waitcnt lgkmcnt(0)
	s_setprio 1
	s_waitcnt lgkmcnt(0)
	v_mfma_f32_16x16x32_bf16 v[126:129], v[232:235], v[158:161], v[126:129]
	v_mfma_f32_16x16x32_bf16 v[122:125], v[240:243], v[158:161], v[122:125]
	v_mfma_f32_16x16x32_bf16 v[118:121], v[232:235], v[166:169], v[118:121]
	v_mfma_f32_16x16x32_bf16 v[114:117], v[240:243], v[166:169], v[114:117]
	v_mfma_f32_16x16x32_bf16 v[110:113], v[232:235], v[178:181], v[110:113]
	v_mfma_f32_16x16x32_bf16 v[106:109], v[240:243], v[178:181], v[106:109]
	v_mfma_f32_16x16x32_bf16 v[102:105], v[232:235], v[186:189], v[102:105]
	v_mfma_f32_16x16x32_bf16 v[98:101], v[240:243], v[186:189], v[98:101]
	v_mfma_f32_16x16x32_bf16 v[126:129], v[236:239], v[162:165], v[126:129]
	v_mfma_f32_16x16x32_bf16 v[122:125], v[244:247], v[162:165], v[122:125]
	v_mfma_f32_16x16x32_bf16 v[118:121], v[236:239], v[170:173], v[118:121]
	v_mfma_f32_16x16x32_bf16 v[114:117], v[244:247], v[170:173], v[114:117]
	v_mfma_f32_16x16x32_bf16 v[110:113], v[236:239], v[182:185], v[110:113]
	v_mfma_f32_16x16x32_bf16 v[106:109], v[244:247], v[182:185], v[106:109]
	v_mfma_f32_16x16x32_bf16 v[102:105], v[236:239], v[192:195], v[102:105]
	v_mfma_f32_16x16x32_bf16 v[98:101], v[244:247], v[192:195], v[98:101]
	s_setprio 0
	s_barrier
	s_add_i32 s0, s57, s49
	v_add_u32_e32 v177, s58, v174
	s_mov_b32 m0, s0
	ds_read_b128 v[196:199], v177
	ds_read_b128 v[200:203], v177 offset:1024
	ds_read_b128 v[204:207], v177 offset:2048
	ds_read_b128 v[208:211], v177 offset:3072
	global_load_lds_dwordx4 v148, s[44:45]
	s_add_i32 m0, s0, 0x2000
	s_nop 0
	global_load_lds_dwordx4 v152, s[44:45]
	s_barrier
	s_waitcnt lgkmcnt(0)
	s_setprio 1
	s_waitcnt lgkmcnt(0)
	v_mfma_f32_16x16x32_bf16 v[94:97], v[196:199], v[158:161], v[94:97]
	v_mfma_f32_16x16x32_bf16 v[90:93], v[204:207], v[158:161], v[90:93]
	v_mfma_f32_16x16x32_bf16 v[86:89], v[196:199], v[166:169], v[86:89]
	v_mfma_f32_16x16x32_bf16 v[82:85], v[204:207], v[166:169], v[82:85]
	v_mfma_f32_16x16x32_bf16 v[78:81], v[196:199], v[178:181], v[78:81]
	v_mfma_f32_16x16x32_bf16 v[74:77], v[204:207], v[178:181], v[74:77]
	v_mfma_f32_16x16x32_bf16 v[70:73], v[196:199], v[186:189], v[70:73]
	v_mfma_f32_16x16x32_bf16 v[66:69], v[204:207], v[186:189], v[66:69]
	v_mfma_f32_16x16x32_bf16 v[94:97], v[200:203], v[162:165], v[94:97]
	v_mfma_f32_16x16x32_bf16 v[90:93], v[208:211], v[162:165], v[90:93]
	v_mfma_f32_16x16x32_bf16 v[86:89], v[200:203], v[170:173], v[86:89]
	v_mfma_f32_16x16x32_bf16 v[82:85], v[208:211], v[170:173], v[82:85]
	v_mfma_f32_16x16x32_bf16 v[78:81], v[200:203], v[182:185], v[78:81]
	v_mfma_f32_16x16x32_bf16 v[74:77], v[208:211], v[182:185], v[74:77]
	v_mfma_f32_16x16x32_bf16 v[70:73], v[200:203], v[192:195], v[70:73]
	v_mfma_f32_16x16x32_bf16 v[66:69], v[208:211], v[192:195], v[66:69]
	s_setprio 0
	s_mov_b32 m0, s50
	s_barrier
	ds_read_b128 v[158:161], v176 offset:16384
	ds_read_b128 v[162:165], v176 offset:17408
	ds_read_b128 v[166:169], v176 offset:18432
	ds_read_b128 v[170:173], v176 offset:19456
	ds_read_b128 v[178:181], v176 offset:20480
	ds_read_b128 v[182:185], v176 offset:21504
	ds_read_b128 v[186:189], v176 offset:22528
	ds_read_b128 v[192:195], v176 offset:23552
	global_load_lds_dwordx4 v146, s[46:47]
	s_mov_b32 m0, s51
	s_nop 0
	global_load_lds_dwordx4 v150, s[46:47]
	s_waitcnt vmcnt(10)
	s_barrier
	s_waitcnt lgkmcnt(0)
	s_setprio 1
	s_waitcnt lgkmcnt(0)
	v_mfma_f32_16x16x32_bf16 v[62:65], v[232:235], v[158:161], v[62:65]
	v_mfma_f32_16x16x32_bf16 v[58:61], v[240:243], v[158:161], v[58:61]
	v_mfma_f32_16x16x32_bf16 v[54:57], v[232:235], v[166:169], v[54:57]
	v_mfma_f32_16x16x32_bf16 v[50:53], v[240:243], v[166:169], v[50:53]
	v_mfma_f32_16x16x32_bf16 v[46:49], v[232:235], v[178:181], v[46:49]
	v_mfma_f32_16x16x32_bf16 v[42:45], v[240:243], v[178:181], v[42:45]
	v_mfma_f32_16x16x32_bf16 v[38:41], v[232:235], v[186:189], v[38:41]
	v_mfma_f32_16x16x32_bf16 v[34:37], v[240:243], v[186:189], v[34:37]
	v_mfma_f32_16x16x32_bf16 v[62:65], v[236:239], v[162:165], v[62:65]
	v_mfma_f32_16x16x32_bf16 v[58:61], v[244:247], v[162:165], v[58:61]
	v_mfma_f32_16x16x32_bf16 v[54:57], v[236:239], v[170:173], v[54:57]
	v_mfma_f32_16x16x32_bf16 v[50:53], v[244:247], v[170:173], v[50:53]
	v_mfma_f32_16x16x32_bf16 v[46:49], v[236:239], v[182:185], v[46:49]
	v_mfma_f32_16x16x32_bf16 v[42:45], v[244:247], v[182:185], v[42:45]
	v_mfma_f32_16x16x32_bf16 v[38:41], v[236:239], v[192:195], v[38:41]
	v_mfma_f32_16x16x32_bf16 v[34:37], v[244:247], v[192:195], v[34:37]
	s_setprio 0
	s_barrier
; #define G_STAGE(bufoff, gbase, voff) do { _Pragma("unroll") for (int _i = 0; _i < 2; ++_i) \
;         __builtin_amdgcn_global_load_lds((const unsigned*)((const char*)(gbase) + (voff)[_i]), (LAS unsigned*)(lds + (bufoff) + ldsw + _i * 8192), 16, 0, 0); } while (0)
; #define G_WAIT_V(n) asm volatile("s_waitcnt vmcnt(" #n ")" ::: "memory")
; #define G_WAIT_L(n) asm volatile("s_waitcnt lgkmcnt(" #n ")" ::: "memory")
; #define G_BAR __builtin_amdgcn_s_barrier()
; #define G_SCHED __builtin_amdgcn_sched_barrier(0)
; template <int MODE  , class Epi, class Sched>
; __device__ __forceinline__ void gemm_phase(LAS unsigned char* lds, const GemmDesc g, const Sched& S, const Epi& E) {
;     ...
;             G_STAGE(G_SB(0, 1), b2 + hstepB, voffB);
;             G_WAIT_V(6); G_BAR; G_MMA(1, 1, At, B1); G_BAR;
;             G_LDB(B0, 1, 0); G_SCHED; G_LDA(At, 1, 0); G_STAGE(G_SA(0, 1), a2 + hstepA, voffA);
;             G_WAIT_L(8); G_BAR; G_WAIT_L(0); G_MMA(0, 0, At, B0); G_BAR; G_SCHED;
;             G_LDB(B1, 1, 1); G_STAGE(G_SB(1, 0), b3, voffB);
;             G_BAR; G_WAIT_L(0); G_MMA(0, 1, At, B1); G_BAR;
	v_add_u32_e32 v142, 0x18000, v174
	ds_read_b128 v[130:133], v142
	ds_read_b128 v[134:137], v142 offset:1024
	ds_read_b128 v[138:141], v142 offset:2048
	ds_read_b128 v[142:145], v142 offset:3072
	s_add_u32 s0, s44, 0x84000
	s_addc_u32 s1, s45, 0
	s_add_i32 s10, s58, s49
	s_mov_b32 m0, s10
	s_nop 0
	global_load_lds_dwordx4 v148, s[0:1]
	s_add_i32 m0, s10, 0x2000
	s_nop 0
	global_load_lds_dwordx4 v152, s[0:1]
	s_waitcnt vmcnt(6)
	s_barrier
	s_setprio 1
	v_mfma_f32_16x16x32_bf16 v[30:33], v[196:199], v[158:161], v[30:33]
	v_mfma_f32_16x16x32_bf16 v[26:29], v[204:207], v[158:161], v[26:29]
	v_mfma_f32_16x16x32_bf16 v[22:25], v[196:199], v[166:169], v[22:25]
	v_mfma_f32_16x16x32_bf16 v[18:21], v[204:207], v[166:169], v[18:21]
	v_mfma_f32_16x16x32_bf16 v[14:17], v[196:199], v[178:181], v[14:17]
	v_mfma_f32_16x16x32_bf16 v[10:13], v[204:207], v[178:181], v[10:13]
	v_mfma_f32_16x16x32_bf16 v[6:9], v[196:199], v[186:189], v[6:9]
	v_mfma_f32_16x16x32_bf16 v[2:5], v[204:207], v[186:189], v[2:5]
	v_mfma_f32_16x16x32_bf16 v[30:33], v[200:203], v[162:165], v[30:33]
	v_mfma_f32_16x16x32_bf16 v[26:29], v[208:211], v[162:165], v[26:29]
	v_mfma_f32_16x16x32_bf16 v[22:25], v[200:203], v[170:173], v[22:25]
	v_mfma_f32_16x16x32_bf16 v[18:21], v[208:211], v[170:173], v[18:21]
	v_mfma_f32_16x16x32_bf16 v[14:17], v[200:203], v[182:185], v[14:17]
	v_mfma_f32_16x16x32_bf16 v[10:13], v[208:211], v[182:185], v[10:13]
	v_mfma_f32_16x16x32_bf16 v[6:9], v[200:203], v[192:195], v[6:9]
	v_mfma_f32_16x16x32_bf16 v[2:5], v[208:211], v[192:195], v[2:5]
	s_setprio 0
	s_add_i32 s10, 0, 0x18000
	s_barrier
	s_add_u32 s0, s46, 0x84000
	s_addc_u32 s1, s47, 0
	s_mov_b32 m0, s52
	ds_read_b128 v[158:161], v176 offset:32768
	ds_read_b128 v[162:165], v176 offset:33792
	ds_read_b128 v[166:169], v176 offset:34816
	ds_read_b128 v[170:173], v176 offset:35840
	ds_read_b128 v[178:181], v176 offset:36864
	ds_read_b128 v[182:185], v176 offset:37888
	ds_read_b128 v[186:189], v176 offset:38912
	ds_read_b128 v[192:195], v176 offset:39936
	global_load_lds_dwordx4 v146, s[0:1]
	s_mov_b32 m0, s53
	s_nop 0
	global_load_lds_dwordx4 v150, s[0:1]
	s_waitcnt lgkmcnt(8)
	s_barrier
	s_waitcnt lgkmcnt(0)
	s_setprio 1
	s_waitcnt lgkmcnt(0)
	v_mfma_f32_16x16x32_bf16 v[126:129], v[130:133], v[158:161], v[126:129]
	v_mfma_f32_16x16x32_bf16 v[122:125], v[138:141], v[158:161], v[122:125]
	v_mfma_f32_16x16x32_bf16 v[118:121], v[130:133], v[166:169], v[118:121]
	v_mfma_f32_16x16x32_bf16 v[114:117], v[138:141], v[166:169], v[114:117]
	v_mfma_f32_16x16x32_bf16 v[110:113], v[130:133], v[178:181], v[110:113]
	v_mfma_f32_16x16x32_bf16 v[106:109], v[138:141], v[178:181], v[106:109]
	v_mfma_f32_16x16x32_bf16 v[102:105], v[130:133], v[186:189], v[102:105]
	v_mfma_f32_16x16x32_bf16 v[98:101], v[138:141], v[186:189], v[98:101]
	v_mfma_f32_16x16x32_bf16 v[126:129], v[134:137], v[162:165], v[126:129]
	v_mfma_f32_16x16x32_bf16 v[122:125], v[142:145], v[162:165], v[122:125]
	v_mfma_f32_16x16x32_bf16 v[118:121], v[134:137], v[170:173], v[118:121]
	v_mfma_f32_16x16x32_bf16 v[114:117], v[142:145], v[170:173], v[114:117]
	v_mfma_f32_16x16x32_bf16 v[110:113], v[134:137], v[182:185], v[110:113]
	v_mfma_f32_16x16x32_bf16 v[106:109], v[142:145], v[182:185], v[106:109]
	v_mfma_f32_16x16x32_bf16 v[102:105], v[134:137], v[192:195], v[102:105]
	v_mfma_f32_16x16x32_bf16 v[98:101], v[142:145], v[192:195], v[98:101]
	s_setprio 0
	s_barrier
	s_add_i32 s11, 0, 0x1c000
	s_add_i32 s0, s10, s49
	v_add_u32_e32 v177, s11, v174
	s_add_u32 s98, s44, 0x80
	s_addc_u32 s99, s45, 0
	s_mov_b32 m0, s0
	ds_read_b128 v[196:199], v177
	ds_read_b128 v[200:203], v177 offset:1024
	ds_read_b128 v[204:207], v177 offset:2048
	ds_read_b128 v[208:211], v177 offset:3072
	global_load_lds_dwordx4 v148, s[98:99]
	s_add_i32 m0, s0, 0x2000
	s_nop 0
	global_load_lds_dwordx4 v152, s[98:99]
	s_barrier
; #define G_STAGE(bufoff, gbase, voff) do { _Pragma("unroll") for (int _i = 0; _i < 2; ++_i) \
;         __builtin_amdgcn_global_load_lds((const unsigned*)((const char*)(gbase) + (voff)[_i]), (LAS unsigned*)(lds + (bufoff) + ldsw + _i * 8192), 16, 0, 0); } while (0)
; #define G_WAIT_V(n) asm volatile("s_waitcnt vmcnt(" #n ")" ::: "memory")
; #define G_WAIT_L(n) asm volatile("s_waitcnt lgkmcnt(" #n ")" ::: "memory")
; #define G_BAR __builtin_amdgcn_s_barrier()
; #define G_SCHED __builtin_amdgcn_sched_barrier(0)
; template <int MODE  , class Epi, class Sched>
; __device__ __forceinline__ void gemm_phase(LAS unsigned char* lds, const GemmDesc g, const Sched& S, const Epi& E) {
;     ...
;             G_LDA(At, 1, 1); G_STAGE(G_SA(1, 0), a3, voffA);
;             G_BAR; G_WAIT_L(0); G_MMA(1, 0, At, B0); G_BAR; G_SCHED;
;             G_STAGE(G_SB(1, 1), b3 + hstepB, voffB);
;             G_WAIT_V(6); G_BAR; G_MMA(1, 1, At, B1); G_BAR;
;         }
	s_waitcnt lgkmcnt(0)
	s_setprio 1
	s_waitcnt lgkmcnt(0)
	v_mfma_f32_16x16x32_bf16 v[94:97], v[196:199], v[158:161], v[94:97]
	v_mfma_f32_16x16x32_bf16 v[90:93], v[204:207], v[158:161], v[90:93]
	v_mfma_f32_16x16x32_bf16 v[86:89], v[196:199], v[166:169], v[86:89]
	v_mfma_f32_16x16x32_bf16 v[82:85], v[204:207], v[166:169], v[82:85]
	v_mfma_f32_16x16x32_bf16 v[78:81], v[196:199], v[178:181], v[78:81]
	v_mfma_f32_16x16x32_bf16 v[74:77], v[204:207], v[178:181], v[74:77]
	v_mfma_f32_16x16x32_bf16 v[70:73], v[196:199], v[186:189], v[70:73]
	v_mfma_f32_16x16x32_bf16 v[66:69], v[204:207], v[186:189], v[66:69]
	v_mfma_f32_16x16x32_bf16 v[94:97], v[200:203], v[162:165], v[94:97]
	v_mfma_f32_16x16x32_bf16 v[90:93], v[208:211], v[162:165], v[90:93]
	v_mfma_f32_16x16x32_bf16 v[86:89], v[200:203], v[170:173], v[86:89]
	v_mfma_f32_16x16x32_bf16 v[82:85], v[208:211], v[170:173], v[82:85]
	v_mfma_f32_16x16x32_bf16 v[78:81], v[200:203], v[182:185], v[78:81]
	v_mfma_f32_16x16x32_bf16 v[74:77], v[208:211], v[182:185], v[74:77]
	v_mfma_f32_16x16x32_bf16 v[70:73], v[200:203], v[192:195], v[70:73]
	v_mfma_f32_16x16x32_bf16 v[66:69], v[208:211], v[192:195], v[66:69]
	s_setprio 0
	s_mov_b32 m0, s54
	s_add_u32 s98, s46, 0x80
	s_addc_u32 s99, s47, 0
	s_barrier
	ds_read_b128 v[158:161], v176 offset:49152
	ds_read_b128 v[162:165], v176 offset:50176
	ds_read_b128 v[166:169], v176 offset:51200
	ds_read_b128 v[170:173], v176 offset:52224
	ds_read_b128 v[178:181], v176 offset:53248
	ds_read_b128 v[182:185], v176 offset:54272
	ds_read_b128 v[186:189], v176 offset:55296
	ds_read_b128 v[192:195], v176 offset:56320
	global_load_lds_dwordx4 v146, s[98:99]
	s_mov_b32 m0, s55
	s_nop 0
	global_load_lds_dwordx4 v150, s[98:99]
	s_waitcnt vmcnt(10)
	s_barrier
	s_waitcnt lgkmcnt(0)
	s_setprio 1
	s_waitcnt lgkmcnt(0)
	v_mfma_f32_16x16x32_bf16 v[62:65], v[130:133], v[158:161], v[62:65]
	v_mfma_f32_16x16x32_bf16 v[58:61], v[138:141], v[158:161], v[58:61]
	v_mfma_f32_16x16x32_bf16 v[54:57], v[130:133], v[166:169], v[54:57]
	v_mfma_f32_16x16x32_bf16 v[50:53], v[138:141], v[166:169], v[50:53]
	v_mfma_f32_16x16x32_bf16 v[46:49], v[130:133], v[178:181], v[46:49]
	v_mfma_f32_16x16x32_bf16 v[42:45], v[138:141], v[178:181], v[42:45]
	v_mfma_f32_16x16x32_bf16 v[38:41], v[130:133], v[186:189], v[38:41]
	v_mfma_f32_16x16x32_bf16 v[34:37], v[138:141], v[186:189], v[34:37]
	v_mfma_f32_16x16x32_bf16 v[62:65], v[134:137], v[162:165], v[62:65]
	v_mfma_f32_16x16x32_bf16 v[58:61], v[142:145], v[162:165], v[58:61]
	v_mfma_f32_16x16x32_bf16 v[54:57], v[134:137], v[170:173], v[54:57]
	v_mfma_f32_16x16x32_bf16 v[50:53], v[142:145], v[170:173], v[50:53]
	v_mfma_f32_16x16x32_bf16 v[46:49], v[134:137], v[182:185], v[46:49]
	v_mfma_f32_16x16x32_bf16 v[42:45], v[142:145], v[182:185], v[42:45]
	v_mfma_f32_16x16x32_bf16 v[38:41], v[134:137], v[192:195], v[38:41]
	v_mfma_f32_16x16x32_bf16 v[34:37], v[142:145], v[192:195], v[34:37]
	s_setprio 0
	s_barrier
	v_add_u32_e32 v244, s57, v174
	ds_read_b128 v[232:235], v244
	ds_read_b128 v[236:239], v244 offset:1024
	ds_read_b128 v[240:243], v244 offset:2048
	ds_read_b128 v[244:247], v244 offset:3072
	s_add_u32 s0, s44, 0x84080
	s_addc_u32 s1, s45, 0
	s_add_i32 s10, s11, s49
	s_mov_b32 m0, s10
	s_nop 0
	global_load_lds_dwordx4 v148, s[0:1]
	s_add_i32 m0, s10, 0x2000
	s_nop 0
	global_load_lds_dwordx4 v152, s[0:1]
	s_waitcnt vmcnt(6)
	s_barrier
	s_setprio 1
	v_mfma_f32_16x16x32_bf16 v[30:33], v[196:199], v[158:161], v[30:33]
	s_add_i32 s71, s71, 2
	s_add_u32 s19, s19, 0x100
	s_addc_u32 s70, s70, 0
	s_cmp_gt_u32 s71, 13
	s_mov_b64 s[40:41], s[42:43]
	v_mfma_f32_16x16x32_bf16 v[26:29], v[204:207], v[158:161], v[26:29]
	v_mfma_f32_16x16x32_bf16 v[22:25], v[196:199], v[166:169], v[22:25]
	v_mfma_f32_16x16x32_bf16 v[18:21], v[204:207], v[166:169], v[18:21]
	v_mfma_f32_16x16x32_bf16 v[14:17], v[196:199], v[178:181], v[14:17]
	v_mfma_f32_16x16x32_bf16 v[10:13], v[204:207], v[178:181], v[10:13]
	v_mfma_f32_16x16x32_bf16 v[6:9], v[196:199], v[186:189], v[6:9]
	v_mfma_f32_16x16x32_bf16 v[2:5], v[204:207], v[186:189], v[2:5]
	v_mfma_f32_16x16x32_bf16 v[30:33], v[200:203], v[162:165], v[30:33]
	v_mfma_f32_16x16x32_bf16 v[26:29], v[208:211], v[162:165], v[26:29]
	v_mfma_f32_16x16x32_bf16 v[22:25], v[200:203], v[170:173], v[22:25]
	v_mfma_f32_16x16x32_bf16 v[18:21], v[208:211], v[170:173], v[18:21]
	v_mfma_f32_16x16x32_bf16 v[14:17], v[200:203], v[182:185], v[14:17]
	v_mfma_f32_16x16x32_bf16 v[10:13], v[208:211], v[182:185], v[10:13]
	v_mfma_f32_16x16x32_bf16 v[6:9], v[200:203], v[192:195], v[6:9]
	v_mfma_f32_16x16x32_bf16 v[2:5], v[208:211], v[192:195], v[2:5]
	s_setprio 0
	s_cbranch_scc1 .Lkdone_sb
	s_barrier
	s_branch .LBB0_897

; __device__ __forceinline__ unsigned pk_bf16(float lo, float hi) { const f32x2_t v = {lo, hi}; return __builtin_bit_cast(unsigned, __builtin_convertvector(v, bf16x2_t)); }
;     __device__ __forceinline__ bool operator()(f32x4 (&acc)[2][2][4][2], const Unit& u, int wr, int wc, int fr, int fq) const {
;         const int r0 = u.pm * BM + wr * 64 + fr, c0 = u.pn * BM + wc * 32 + fq * 8;
; #pragma unroll
;         for (int ai = 0; ai < 2; ++ai)
; #pragma unroll
;             for (int m = 0; m < 4; ++m) { bf16_t* rowp = DL + (size_t)(r0 + ai * HALF + m * 16) * LDP + c0;
; #pragma unroll
;                 for (int bj = 0; bj < 2; ++bj) { const f32x4 v0 = acc[ai][bj][m][0], v1 = acc[ai][bj][m][1];
;                     u32x4 w; w.x = pk_bf16(v0[0], v0[1]); w.y = pk_bf16(v0[2], v0[3]); w.z = pk_bf16(v1[0], v1[1]); w.w = pk_bf16(v1[2], v1[3]);
;                     *(u32x4*)(rowp + bj * HALF) = w; } }
;     __device__ __forceinline__ bool operator()(f32x4 (&acc)[2][2][4][2], const Unit& u, int wr, int wc, int fr, int fq) const {
;         if (u.type == 0) return d(acc, u, wr, wc, fr, fq);
;         if (u.kh == 0) return false;
;         return e(acc, u, wr, wc, fr, fq);
.Lkepi_sb:
	s_waitcnt lgkmcnt(0)
	s_cmp_lg_u32 s67, 0
	s_cbranch_scc0 .LBB0_906
	s_mov_b64 s[42:43], 0
	s_cmp_lg_u32 s66, 0
	s_mov_b64 s[40:41], 0
	s_cbranch_scc0 .LBB0_901
	v_lshl_or_b32 v130, s64, 8, v175
	v_lshl_add_u32 v140, s65, 8, v1
	v_ashrrev_i32_e32 v131, 31, v130
	v_mov_b64_e32 v[134:135], s[26:27]
	v_mad_i64_i32 v[132:133], s[0:1], v140, s59, v[134:135]
	v_lshlrev_b64 v[136:137], 1, v[130:131]
	v_lshl_add_u64 v[138:139], v[132:133], 0, v[136:137]
	v_cvt_pk_bf16_f32 v130, v126, v127
	v_cvt_pk_bf16_f32 v131, v128, v129
	v_cvt_pk_bf16_f32 v132, v122, v123
	v_cvt_pk_bf16_f32 v133, v124, v125
	global_store_dwordx4 v[138:139], v[130:133], off
	s_mov_b64 s[40:41], -1
	s_nop 0
	v_cvt_pk_bf16_f32 v130, v94, v95
	v_cvt_pk_bf16_f32 v131, v96, v97
	v_cvt_pk_bf16_f32 v132, v90, v91
	v_cvt_pk_bf16_f32 v133, v92, v93
	global_store_dwordx4 v[138:139], v[130:133], off offset:256
	s_nop 1
	v_or_b32_e32 v130, 16, v140
	v_mad_i64_i32 v[130:131], s[0:1], v130, s59, v[134:135]
	v_lshl_add_u64 v[138:139], v[130:131], 0, v[136:137]
	v_cvt_pk_bf16_f32 v130, v118, v119
	v_cvt_pk_bf16_f32 v131, v120, v121
	v_cvt_pk_bf16_f32 v132, v114, v115
	v_cvt_pk_bf16_f32 v133, v116, v117
	global_store_dwordx4 v[138:139], v[130:133], off
	s_nop 1
	v_cvt_pk_bf16_f32 v130, v86, v87
	v_cvt_pk_bf16_f32 v131, v88, v89
	v_cvt_pk_bf16_f32 v132, v82, v83
	v_cvt_pk_bf16_f32 v133, v84, v85
	global_store_dwordx4 v[138:139], v[130:133], off offset:256
	s_nop 1
	v_or_b32_e32 v130, 32, v140
	v_mad_i64_i32 v[130:131], s[0:1], v130, s59, v[134:135]
	v_lshl_add_u64 v[138:139], v[130:131], 0, v[136:137]
	v_cvt_pk_bf16_f32 v130, v110, v111
	v_cvt_pk_bf16_f32 v131, v112, v113
	v_cvt_pk_bf16_f32 v132, v106, v107
	v_cvt_pk_bf16_f32 v133, v108, v109
	global_store_dwordx4 v[138:139], v[130:133], off
	s_nop 1
	v_cvt_pk_bf16_f32 v130, v78, v79
	v_cvt_pk_bf16_f32 v131, v80, v81
	v_cvt_pk_bf16_f32 v132, v74, v75
	v_cvt_pk_bf16_f32 v133, v76, v77
	global_store_dwordx4 v[138:139], v[130:133], off offset:256
	s_nop 1
	v_or_b32_e32 v130, 48, v140
	v_mad_i64_i32 v[130:131], s[0:1], v130, s59, v[134:135]
	v_lshl_add_u64 v[138:139], v[130:131], 0, v[136:137]
	v_cvt_pk_bf16_f32 v130, v102, v103
	v_cvt_pk_bf16_f32 v131, v104, v105
	v_cvt_pk_bf16_f32 v132, v98, v99
	v_cvt_pk_bf16_f32 v133, v100, v101
	global_store_dwordx4 v[138:139], v[130:133], off
	s_nop 1
	v_cvt_pk_bf16_f32 v130, v70, v71
	v_cvt_pk_bf16_f32 v131, v72, v73
	v_cvt_pk_bf16_f32 v132, v66, v67
	v_cvt_pk_bf16_f32 v133, v68, v69
	global_store_dwordx4 v[138:139], v[130:133], off offset:256
	s_nop 1
	v_add_u32_e32 v130, 0x80, v140
	v_mad_i64_i32 v[130:131], s[0:1], v130, s59, v[134:135]
	v_lshl_add_u64 v[138:139], v[130:131], 0, v[136:137]
	v_cvt_pk_bf16_f32 v130, v62, v63
	v_cvt_pk_bf16_f32 v131, v64, v65
	v_cvt_pk_bf16_f32 v132, v58, v59
	v_cvt_pk_bf16_f32 v133, v60, v61
	global_store_dwordx4 v[138:139], v[130:133], off
	s_nop 1
	v_cvt_pk_bf16_f32 v130, v30, v31
	v_cvt_pk_bf16_f32 v131, v32, v33
	v_cvt_pk_bf16_f32 v132, v26, v27
	v_cvt_pk_bf16_f32 v133, v28, v29
	global_store_dwordx4 v[138:139], v[130:133], off offset:256
	s_nop 1
	v_add_u32_e32 v130, 0x90, v140
	v_mad_i64_i32 v[130:131], s[0:1], v130, s59, v[134:135]
	v_lshl_add_u64 v[138:139], v[130:131], 0, v[136:137]
	v_cvt_pk_bf16_f32 v130, v54, v55
	v_cvt_pk_bf16_f32 v131, v56, v57
	v_cvt_pk_bf16_f32 v132, v50, v51
	v_cvt_pk_bf16_f32 v133, v52, v53
	global_store_dwordx4 v[138:139], v[130:133], off
	s_nop 1
	v_cvt_pk_bf16_f32 v130, v22, v23
	v_cvt_pk_bf16_f32 v131, v24, v25
	v_cvt_pk_bf16_f32 v132, v18, v19
	v_cvt_pk_bf16_f32 v133, v20, v21
	global_store_dwordx4 v[138:139], v[130:133], off offset:256
	s_nop 1
	v_add_u32_e32 v130, 0xa0, v140
	v_mad_i64_i32 v[130:131], s[0:1], v130, s59, v[134:135]
	v_lshl_add_u64 v[138:139], v[130:131], 0, v[136:137]
	v_cvt_pk_bf16_f32 v130, v46, v47
	v_cvt_pk_bf16_f32 v131, v48, v49
	v_cvt_pk_bf16_f32 v132, v42, v43
	v_cvt_pk_bf16_f32 v133, v44, v45
	global_store_dwordx4 v[138:139], v[130:133], off
	s_nop 1
	v_cvt_pk_bf16_f32 v130, v14, v15
	v_cvt_pk_bf16_f32 v131, v16, v17
	v_cvt_pk_bf16_f32 v132, v10, v11
	v_cvt_pk_bf16_f32 v133, v12, v13
	global_store_dwordx4 v[138:139], v[130:133], off offset:256
	s_nop 1
	v_add_u32_e32 v130, 0xb0, v140
	v_mad_i64_i32 v[130:131], s[0:1], v130, s59, v[134:135]
	v_lshl_add_u64 v[130:131], v[130:131], 0, v[136:137]
	v_cvt_pk_bf16_f32 v132, v38, v39
	v_cvt_pk_bf16_f32 v133, v40, v41
	v_cvt_pk_bf16_f32 v134, v34, v35
	v_cvt_pk_bf16_f32 v135, v36, v37
	global_store_dwordx4 v[130:131], v[132:135], off

; #define G_STAGE(bufoff, gbase, voff) do { _Pragma("unroll") for (int _i = 0; _i < 2; ++_i) \
;         __builtin_amdgcn_global_load_lds((const unsigned*)((const char*)(gbase) + (voff)[_i]), (LAS unsigned*)(lds + (bufoff) + ldsw + _i * 8192), 16, 0, 0); } while (0)
; #define G_WAIT_L(n) asm volatile("s_waitcnt lgkmcnt(" #n ")" ::: "memory")
; #define G_BAR __builtin_amdgcn_s_barrier()
; #define G_SCHED __builtin_amdgcn_sched_barrier(0)
; template <int MODE  , class Epi, class Sched>
; __device__ __forceinline__ void gemm_phase(LAS unsigned char* lds, const GemmDesc g, const Sched& S, const Epi& E) {
;     ...
;             G_LDB(B0, 0, 0); G_SCHED; G_LDA(At, 0, 0); G_STAGE(G_SA(1, 1), a1 + hstepA, voffA);
;             G_WAIT_L(8); G_BAR; G_WAIT_L(0); G_MMA(0, 0, At, B0); G_BAR; G_SCHED;
;             G_LDB(B1, 0, 1); G_STAGE(G_SB(0, 0), b2, voffB);
;             G_BAR; G_WAIT_L(0); G_MMA(0, 1, At, B1); G_BAR;
;             G_LDA(At, 0, 1); G_STAGE(G_SA(0, 0), a2, voffA);
;             G_BAR; G_WAIT_L(0); G_MMA(1, 0, At, B0); G_BAR; G_SCHED;
.Lnodb_sc:
	v_add_u32_e32 v145, s50, v142
	ds_read_b128 v[232:235], v145
	ds_read_b128 v[236:239], v145 offset:1024
	ds_read_b128 v[240:243], v145 offset:2048
	ds_read_b128 v[244:247], v145 offset:3072
.LBB0_987:
	s_add_u32 s34, s20, 0x100
	s_addc_u32 s35, s21, 0
	s_cmp_eq_u32 s60, 12
	s_cselect_b32 s43, s17, s35
	s_cselect_b32 s42, s16, s34
	s_cselect_b32 s41, s3, s59
	s_cselect_b32 s40, s2, s15
	s_add_u32 s98, s20, 0x84080
	s_addc_u32 s99, s21, 0
	s_add_i32 m0, s44, 0xc000
	ds_read_b128 v[162:165], v144
	ds_read_b128 v[166:169], v144 offset:1024
	ds_read_b128 v[170:173], v144 offset:2048
	ds_read_b128 v[174:177], v144 offset:3072
	ds_read_b128 v[178:181], v144 offset:4096
	ds_read_b128 v[182:185], v144 offset:5120
	ds_read_b128 v[186:189], v144 offset:6144
	ds_read_b128 v[192:195], v144 offset:7168
	global_load_lds_dwordx4 v130, s[98:99]
	s_add_i32 m0, s44, 0xe000
	s_nop 0
	global_load_lds_dwordx4 v134, s[98:99]
	s_waitcnt lgkmcnt(8)
	s_barrier
	s_waitcnt lgkmcnt(0)
	s_setprio 1
	s_waitcnt lgkmcnt(0)
	v_mfma_f32_16x16x32_bf16 v[126:129], v[232:235], v[162:165], v[126:129]
	v_mfma_f32_16x16x32_bf16 v[122:125], v[240:243], v[162:165], v[122:125]
	v_mfma_f32_16x16x32_bf16 v[118:121], v[232:235], v[170:173], v[118:121]
	v_mfma_f32_16x16x32_bf16 v[114:117], v[240:243], v[170:173], v[114:117]
	v_mfma_f32_16x16x32_bf16 v[110:113], v[232:235], v[178:181], v[110:113]
	v_mfma_f32_16x16x32_bf16 v[106:109], v[240:243], v[178:181], v[106:109]
	v_mfma_f32_16x16x32_bf16 v[102:105], v[232:235], v[186:189], v[102:105]
	v_mfma_f32_16x16x32_bf16 v[98:101], v[240:243], v[186:189], v[98:101]
	v_mfma_f32_16x16x32_bf16 v[126:129], v[236:239], v[166:169], v[126:129]
	v_mfma_f32_16x16x32_bf16 v[122:125], v[244:247], v[166:169], v[122:125]
	v_mfma_f32_16x16x32_bf16 v[118:121], v[236:239], v[174:177], v[118:121]
	v_mfma_f32_16x16x32_bf16 v[114:117], v[244:247], v[174:177], v[114:117]
	v_mfma_f32_16x16x32_bf16 v[110:113], v[236:239], v[182:185], v[110:113]
	v_mfma_f32_16x16x32_bf16 v[106:109], v[244:247], v[182:185], v[106:109]
	v_mfma_f32_16x16x32_bf16 v[102:105], v[236:239], v[192:195], v[102:105]
	v_mfma_f32_16x16x32_bf16 v[98:101], v[244:247], v[192:195], v[98:101]
	s_setprio 0
	s_barrier
	s_add_i32 s0, s50, s31
	v_add_u32_e32 v145, s51, v142
	s_mov_b32 m0, s0
	ds_read_b128 v[196:199], v145
	ds_read_b128 v[200:203], v145 offset:1024
	ds_read_b128 v[204:207], v145 offset:2048
	ds_read_b128 v[208:211], v145 offset:3072
	global_load_lds_dwordx4 v132, s[40:41]
	s_add_i32 m0, s0, 0x2000
	s_nop 0
	global_load_lds_dwordx4 v136, s[40:41]
	s_barrier
	s_waitcnt lgkmcnt(0)
	s_setprio 1
	s_waitcnt lgkmcnt(0)
	v_mfma_f32_16x16x32_bf16 v[94:97], v[196:199], v[162:165], v[94:97]
	v_mfma_f32_16x16x32_bf16 v[90:93], v[204:207], v[162:165], v[90:93]
	v_mfma_f32_16x16x32_bf16 v[86:89], v[196:199], v[170:173], v[86:89]
	v_mfma_f32_16x16x32_bf16 v[82:85], v[204:207], v[170:173], v[82:85]
	v_mfma_f32_16x16x32_bf16 v[78:81], v[196:199], v[178:181], v[78:81]
	v_mfma_f32_16x16x32_bf16 v[74:77], v[204:207], v[178:181], v[74:77]
	v_mfma_f32_16x16x32_bf16 v[70:73], v[196:199], v[186:189], v[70:73]
	v_mfma_f32_16x16x32_bf16 v[66:69], v[204:207], v[186:189], v[66:69]
	v_mfma_f32_16x16x32_bf16 v[94:97], v[200:203], v[166:169], v[94:97]
	v_mfma_f32_16x16x32_bf16 v[90:93], v[208:211], v[166:169], v[90:93]
	v_mfma_f32_16x16x32_bf16 v[86:89], v[200:203], v[174:177], v[86:89]
	v_mfma_f32_16x16x32_bf16 v[82:85], v[208:211], v[174:177], v[82:85]
	v_mfma_f32_16x16x32_bf16 v[78:81], v[200:203], v[182:185], v[78:81]
	v_mfma_f32_16x16x32_bf16 v[74:77], v[208:211], v[182:185], v[74:77]
	v_mfma_f32_16x16x32_bf16 v[70:73], v[200:203], v[192:195], v[70:73]
	v_mfma_f32_16x16x32_bf16 v[66:69], v[208:211], v[192:195], v[66:69]
	s_setprio 0
	s_mov_b32 m0, s44
	s_barrier
	ds_read_b128 v[162:165], v144 offset:16384
	ds_read_b128 v[166:169], v144 offset:17408
	ds_read_b128 v[170:173], v144 offset:18432
	ds_read_b128 v[174:177], v144 offset:19456
	ds_read_b128 v[178:181], v144 offset:20480
	ds_read_b128 v[182:185], v144 offset:21504
	ds_read_b128 v[186:189], v144 offset:22528
	ds_read_b128 v[192:195], v144 offset:23552
	global_load_lds_dwordx4 v130, s[42:43]
	s_mov_b32 m0, s45
	s_nop 0
	global_load_lds_dwordx4 v134, s[42:43]
	s_waitcnt vmcnt(10)
	s_barrier
	s_waitcnt lgkmcnt(0)
	s_setprio 1
	s_waitcnt lgkmcnt(0)
	v_mfma_f32_16x16x32_bf16 v[62:65], v[232:235], v[162:165], v[62:65]
	v_mfma_f32_16x16x32_bf16 v[58:61], v[240:243], v[162:165], v[58:61]
	v_mfma_f32_16x16x32_bf16 v[54:57], v[232:235], v[170:173], v[54:57]
	v_mfma_f32_16x16x32_bf16 v[50:53], v[240:243], v[170:173], v[50:53]
	v_mfma_f32_16x16x32_bf16 v[46:49], v[232:235], v[178:181], v[46:49]
	v_mfma_f32_16x16x32_bf16 v[42:45], v[240:243], v[178:181], v[42:45]
	v_mfma_f32_16x16x32_bf16 v[38:41], v[232:235], v[186:189], v[38:41]
	v_mfma_f32_16x16x32_bf16 v[34:37], v[240:243], v[186:189], v[34:37]
	v_mfma_f32_16x16x32_bf16 v[62:65], v[236:239], v[166:169], v[62:65]
	v_mfma_f32_16x16x32_bf16 v[58:61], v[244:247], v[166:169], v[58:61]
	v_mfma_f32_16x16x32_bf16 v[54:57], v[236:239], v[174:177], v[54:57]
	v_mfma_f32_16x16x32_bf16 v[50:53], v[244:247], v[174:177], v[50:53]
	v_mfma_f32_16x16x32_bf16 v[46:49], v[236:239], v[182:185], v[46:49]
	v_mfma_f32_16x16x32_bf16 v[42:45], v[244:247], v[182:185], v[42:45]
	v_mfma_f32_16x16x32_bf16 v[38:41], v[236:239], v[192:195], v[38:41]
	v_mfma_f32_16x16x32_bf16 v[34:37], v[244:247], v[192:195], v[34:37]
	s_setprio 0
	s_barrier
; #define G_STAGE(bufoff, gbase, voff) do { _Pragma("unroll") for (int _i = 0; _i < 2; ++_i) \
;         __builtin_amdgcn_global_load_lds((const unsigned*)((const char*)(gbase) + (voff)[_i]), (LAS unsigned*)(lds + (bufoff) + ldsw + _i * 8192), 16, 0, 0); } while (0)
; #define G_WAIT_V(n) asm volatile("s_waitcnt vmcnt(" #n ")" ::: "memory")
; #define G_WAIT_L(n) asm volatile("s_waitcnt lgkmcnt(" #n ")" ::: "memory")
; #define G_BAR __builtin_amdgcn_s_barrier()
; #define G_SCHED __builtin_amdgcn_sched_barrier(0)
; template <int MODE  , class Epi, class Sched>
; __device__ __forceinline__ void gemm_phase(LAS unsigned char* lds, const GemmDesc g, const Sched& S, const Epi& E) {
;     ...
;             G_STAGE(G_SB(0, 1), b2 + hstepB, voffB);
;             G_WAIT_V(6); G_BAR; G_MMA(1, 1, At, B1); G_BAR;
;             G_LDB(B0, 1, 0); G_SCHED; G_LDA(At, 1, 0); G_STAGE(G_SA(0, 1), a2 + hstepA, voffA);
;             G_WAIT_L(8); G_BAR; G_WAIT_L(0); G_MMA(0, 0, At, B0); G_BAR; G_SCHED;
;             G_LDB(B1, 1, 1); G_STAGE(G_SB(1, 0), b3, voffB);
;             G_BAR; G_WAIT_L(0); G_MMA(0, 1, At, B1); G_BAR;
	v_add_u32_e32 v145, 0x18000, v142
	ds_read_b128 v[146:149], v145
	ds_read_b128 v[150:153], v145 offset:1024
	ds_read_b128 v[154:157], v145 offset:2048
	ds_read_b128 v[158:161], v145 offset:3072
	s_add_u32 s0, s40, 0x84000
	s_addc_u32 s1, s41, 0
	s_add_i32 s10, s51, s31
	s_mov_b32 m0, s10
	s_nop 0
	global_load_lds_dwordx4 v132, s[0:1]
	s_add_i32 m0, s10, 0x2000
	s_nop 0
	global_load_lds_dwordx4 v136, s[0:1]
	s_waitcnt vmcnt(6)
	s_barrier
	s_setprio 1
	v_mfma_f32_16x16x32_bf16 v[30:33], v[196:199], v[162:165], v[30:33]
	v_mfma_f32_16x16x32_bf16 v[26:29], v[204:207], v[162:165], v[26:29]
	v_mfma_f32_16x16x32_bf16 v[22:25], v[196:199], v[170:173], v[22:25]
	v_mfma_f32_16x16x32_bf16 v[18:21], v[204:207], v[170:173], v[18:21]
	v_mfma_f32_16x16x32_bf16 v[14:17], v[196:199], v[178:181], v[14:17]
	v_mfma_f32_16x16x32_bf16 v[10:13], v[204:207], v[178:181], v[10:13]
	v_mfma_f32_16x16x32_bf16 v[6:9], v[196:199], v[186:189], v[6:9]
	v_mfma_f32_16x16x32_bf16 v[2:5], v[204:207], v[186:189], v[2:5]
	v_mfma_f32_16x16x32_bf16 v[30:33], v[200:203], v[166:169], v[30:33]
	v_mfma_f32_16x16x32_bf16 v[26:29], v[208:211], v[166:169], v[26:29]
	v_mfma_f32_16x16x32_bf16 v[22:25], v[200:203], v[174:177], v[22:25]
	v_mfma_f32_16x16x32_bf16 v[18:21], v[208:211], v[174:177], v[18:21]
	v_mfma_f32_16x16x32_bf16 v[14:17], v[200:203], v[182:185], v[14:17]
	v_mfma_f32_16x16x32_bf16 v[10:13], v[208:211], v[182:185], v[10:13]
	v_mfma_f32_16x16x32_bf16 v[6:9], v[200:203], v[192:195], v[6:9]
	v_mfma_f32_16x16x32_bf16 v[2:5], v[208:211], v[192:195], v[2:5]
	s_setprio 0
	s_add_i32 s10, 0, 0x18000
	s_barrier
	s_add_u32 s0, s42, 0x84000
	s_addc_u32 s1, s43, 0
	s_mov_b32 m0, s46
	ds_read_b128 v[162:165], v144 offset:32768
	ds_read_b128 v[166:169], v144 offset:33792
	ds_read_b128 v[170:173], v144 offset:34816
	ds_read_b128 v[174:177], v144 offset:35840
	ds_read_b128 v[178:181], v144 offset:36864
	ds_read_b128 v[182:185], v144 offset:37888
	ds_read_b128 v[186:189], v144 offset:38912
	ds_read_b128 v[192:195], v144 offset:39936
	global_load_lds_dwordx4 v130, s[0:1]
	s_mov_b32 m0, s47
	s_nop 0
	global_load_lds_dwordx4 v134, s[0:1]
	s_waitcnt lgkmcnt(8)
	s_barrier
	s_waitcnt lgkmcnt(0)
	s_setprio 1
	s_waitcnt lgkmcnt(0)
	v_mfma_f32_16x16x32_bf16 v[126:129], v[146:149], v[162:165], v[126:129]
	v_mfma_f32_16x16x32_bf16 v[122:125], v[154:157], v[162:165], v[122:125]
	v_mfma_f32_16x16x32_bf16 v[118:121], v[146:149], v[170:173], v[118:121]
	v_mfma_f32_16x16x32_bf16 v[114:117], v[154:157], v[170:173], v[114:117]
	v_mfma_f32_16x16x32_bf16 v[110:113], v[146:149], v[178:181], v[110:113]
	v_mfma_f32_16x16x32_bf16 v[106:109], v[154:157], v[178:181], v[106:109]
	v_mfma_f32_16x16x32_bf16 v[102:105], v[146:149], v[186:189], v[102:105]
	v_mfma_f32_16x16x32_bf16 v[98:101], v[154:157], v[186:189], v[98:101]
	v_mfma_f32_16x16x32_bf16 v[126:129], v[150:153], v[166:169], v[126:129]
	v_mfma_f32_16x16x32_bf16 v[122:125], v[158:161], v[166:169], v[122:125]
	v_mfma_f32_16x16x32_bf16 v[118:121], v[150:153], v[174:177], v[118:121]
	v_mfma_f32_16x16x32_bf16 v[114:117], v[158:161], v[174:177], v[114:117]
	v_mfma_f32_16x16x32_bf16 v[110:113], v[150:153], v[182:185], v[110:113]
	v_mfma_f32_16x16x32_bf16 v[106:109], v[158:161], v[182:185], v[106:109]
	v_mfma_f32_16x16x32_bf16 v[102:105], v[150:153], v[192:195], v[102:105]
	v_mfma_f32_16x16x32_bf16 v[98:101], v[158:161], v[192:195], v[98:101]
	s_setprio 0
	s_barrier
	s_add_i32 s11, 0, 0x1c000
	s_add_i32 s0, s10, s31
	v_add_u32_e32 v145, s11, v142
	s_add_u32 s98, s40, 0x80
	s_addc_u32 s99, s41, 0
	s_mov_b32 m0, s0
	ds_read_b128 v[196:199], v145
	ds_read_b128 v[200:203], v145 offset:1024
	ds_read_b128 v[204:207], v145 offset:2048
	ds_read_b128 v[208:211], v145 offset:3072
	global_load_lds_dwordx4 v132, s[98:99]
	s_add_i32 m0, s0, 0x2000
	s_nop 0
	global_load_lds_dwordx4 v136, s[98:99]
	s_barrier
; #define G_STAGE(bufoff, gbase, voff) do { _Pragma("unroll") for (int _i = 0; _i < 2; ++_i) \
;         __builtin_amdgcn_global_load_lds((const unsigned*)((const char*)(gbase) + (voff)[_i]), (LAS unsigned*)(lds + (bufoff) + ldsw + _i * 8192), 16, 0, 0); } while (0)
; #define G_WAIT_V(n) asm volatile("s_waitcnt vmcnt(" #n ")" ::: "memory")
; #define G_WAIT_L(n) asm volatile("s_waitcnt lgkmcnt(" #n ")" ::: "memory")
; #define G_BAR __builtin_amdgcn_s_barrier()
; #define G_SCHED __builtin_amdgcn_sched_barrier(0)
; template <int MODE  , class Epi, class Sched>
; __device__ __forceinline__ void gemm_phase(LAS unsigned char* lds, const GemmDesc g, const Sched& S, const Epi& E) {
;     ...
;             G_LDA(At, 1, 1); G_STAGE(G_SA(1, 0), a3, voffA);
;             G_BAR; G_WAIT_L(0); G_MMA(1, 0, At, B0); G_BAR; G_SCHED;
;             G_STAGE(G_SB(1, 1), b3 + hstepB, voffB);
;             G_WAIT_V(6); G_BAR; G_MMA(1, 1, At, B1); G_BAR;
;         }
	s_waitcnt lgkmcnt(0)
	s_setprio 1
	s_waitcnt lgkmcnt(0)
	v_mfma_f32_16x16x32_bf16 v[94:97], v[196:199], v[162:165], v[94:97]
	v_mfma_f32_16x16x32_bf16 v[90:93], v[204:207], v[162:165], v[90:93]
	v_mfma_f32_16x16x32_bf16 v[86:89], v[196:199], v[170:173], v[86:89]
	v_mfma_f32_16x16x32_bf16 v[82:85], v[204:207], v[170:173], v[82:85]
	v_mfma_f32_16x16x32_bf16 v[78:81], v[196:199], v[178:181], v[78:81]
	v_mfma_f32_16x16x32_bf16 v[74:77], v[204:207], v[178:181], v[74:77]
	v_mfma_f32_16x16x32_bf16 v[70:73], v[196:199], v[186:189], v[70:73]
	v_mfma_f32_16x16x32_bf16 v[66:69], v[204:207], v[186:189], v[66:69]
	v_mfma_f32_16x16x32_bf16 v[94:97], v[200:203], v[166:169], v[94:97]
	v_mfma_f32_16x16x32_bf16 v[90:93], v[208:211], v[166:169], v[90:93]
	v_mfma_f32_16x16x32_bf16 v[86:89], v[200:203], v[174:177], v[86:89]
	v_mfma_f32_16x16x32_bf16 v[82:85], v[208:211], v[174:177], v[82:85]
	v_mfma_f32_16x16x32_bf16 v[78:81], v[200:203], v[182:185], v[78:81]
	v_mfma_f32_16x16x32_bf16 v[74:77], v[208:211], v[182:185], v[74:77]
	v_mfma_f32_16x16x32_bf16 v[70:73], v[200:203], v[192:195], v[70:73]
	v_mfma_f32_16x16x32_bf16 v[66:69], v[208:211], v[192:195], v[66:69]
	s_setprio 0
	s_mov_b32 m0, s48
	s_add_u32 s98, s42, 0x80
	s_addc_u32 s99, s43, 0
	s_barrier
	ds_read_b128 v[162:165], v144 offset:49152
	ds_read_b128 v[166:169], v144 offset:50176
	ds_read_b128 v[170:173], v144 offset:51200
	ds_read_b128 v[174:177], v144 offset:52224
	ds_read_b128 v[178:181], v144 offset:53248
	ds_read_b128 v[182:185], v144 offset:54272
	ds_read_b128 v[186:189], v144 offset:55296
	ds_read_b128 v[192:195], v144 offset:56320
	global_load_lds_dwordx4 v130, s[98:99]
	s_mov_b32 m0, s49
	s_nop 0
	global_load_lds_dwordx4 v134, s[98:99]
	s_waitcnt vmcnt(10)
	s_barrier
	s_waitcnt lgkmcnt(0)
	s_setprio 1
	s_waitcnt lgkmcnt(0)
	v_mfma_f32_16x16x32_bf16 v[62:65], v[146:149], v[162:165], v[62:65]
	v_mfma_f32_16x16x32_bf16 v[58:61], v[154:157], v[162:165], v[58:61]
	v_mfma_f32_16x16x32_bf16 v[54:57], v[146:149], v[170:173], v[54:57]
	v_mfma_f32_16x16x32_bf16 v[50:53], v[154:157], v[170:173], v[50:53]
	v_mfma_f32_16x16x32_bf16 v[46:49], v[146:149], v[178:181], v[46:49]
	v_mfma_f32_16x16x32_bf16 v[42:45], v[154:157], v[178:181], v[42:45]
	v_mfma_f32_16x16x32_bf16 v[38:41], v[146:149], v[186:189], v[38:41]
	v_mfma_f32_16x16x32_bf16 v[34:37], v[154:157], v[186:189], v[34:37]
	v_mfma_f32_16x16x32_bf16 v[62:65], v[150:153], v[166:169], v[62:65]
	v_mfma_f32_16x16x32_bf16 v[58:61], v[158:161], v[166:169], v[58:61]
	v_mfma_f32_16x16x32_bf16 v[54:57], v[150:153], v[174:177], v[54:57]
	v_mfma_f32_16x16x32_bf16 v[50:53], v[158:161], v[174:177], v[50:53]
	v_mfma_f32_16x16x32_bf16 v[46:49], v[150:153], v[182:185], v[46:49]
	v_mfma_f32_16x16x32_bf16 v[42:45], v[158:161], v[182:185], v[42:45]
	v_mfma_f32_16x16x32_bf16 v[38:41], v[150:153], v[192:195], v[38:41]
	v_mfma_f32_16x16x32_bf16 v[34:37], v[158:161], v[192:195], v[34:37]
	s_setprio 0
	s_barrier
	v_add_u32_e32 v145, s50, v142
	ds_read_b128 v[232:235], v145
	ds_read_b128 v[236:239], v145 offset:1024
	ds_read_b128 v[240:243], v145 offset:2048
	ds_read_b128 v[244:247], v145 offset:3072
	s_add_u32 s0, s40, 0x84080
	s_addc_u32 s1, s41, 0
	s_add_i32 s10, s11, s31
	s_mov_b32 m0, s10
	s_nop 0
	global_load_lds_dwordx4 v132, s[0:1]
	s_add_i32 m0, s10, 0x2000
	s_nop 0
	global_load_lds_dwordx4 v136, s[0:1]
	s_waitcnt vmcnt(6)
	s_barrier
	s_setprio 1
	v_mfma_f32_16x16x32_bf16 v[30:33], v[196:199], v[162:165], v[30:33]
	s_add_i32 s60, s60, 2
	s_add_u32 s15, s15, 0x100
	s_addc_u32 s59, s59, 0
	s_cmp_gt_u32 s60, 13
	s_mov_b64 s[20:21], s[34:35]
	v_mfma_f32_16x16x32_bf16 v[26:29], v[204:207], v[162:165], v[26:29]
	v_mfma_f32_16x16x32_bf16 v[22:25], v[196:199], v[170:173], v[22:25]
	v_mfma_f32_16x16x32_bf16 v[18:21], v[204:207], v[170:173], v[18:21]
	v_mfma_f32_16x16x32_bf16 v[14:17], v[196:199], v[178:181], v[14:17]
	v_mfma_f32_16x16x32_bf16 v[10:13], v[204:207], v[178:181], v[10:13]
	v_mfma_f32_16x16x32_bf16 v[6:9], v[196:199], v[186:189], v[6:9]
	v_mfma_f32_16x16x32_bf16 v[2:5], v[204:207], v[186:189], v[2:5]
	v_mfma_f32_16x16x32_bf16 v[30:33], v[200:203], v[166:169], v[30:33]
	v_mfma_f32_16x16x32_bf16 v[26:29], v[208:211], v[166:169], v[26:29]
	v_mfma_f32_16x16x32_bf16 v[22:25], v[200:203], v[174:177], v[22:25]
	v_mfma_f32_16x16x32_bf16 v[18:21], v[208:211], v[174:177], v[18:21]
	v_mfma_f32_16x16x32_bf16 v[14:17], v[200:203], v[182:185], v[14:17]
	v_mfma_f32_16x16x32_bf16 v[10:13], v[208:211], v[182:185], v[10:13]
	v_mfma_f32_16x16x32_bf16 v[6:9], v[200:203], v[192:195], v[6:9]
	v_mfma_f32_16x16x32_bf16 v[2:5], v[208:211], v[192:195], v[2:5]
	s_setprio 0
	s_cbranch_scc1 .Lkdone_sc
	s_barrier
	s_branch .LBB0_987

; __device__ __forceinline__ unsigned pk_bf16(float lo, float hi) { const f32x2_t v = {lo, hi}; return __builtin_bit_cast(unsigned, __builtin_convertvector(v, bf16x2_t)); }
;     __device__ __forceinline__ bool operator()(f32x4 (&acc)[2][2][4][2], const Unit& u, int wr, int wc, int fr, int fq) const {
;         const int r0 = u.pm * BM + wr * 64 + fr, c0 = u.pn * BM + wc * 32 + fq * 8;
; #pragma unroll
;         for (int ai = 0; ai < 2; ++ai)
; #pragma unroll
;             for (int m = 0; m < 4; ++m) { bf16_t* rowp = DL + (size_t)(r0 + ai * HALF + m * 16) * LDP + c0;
; #pragma unroll
;                 for (int bj = 0; bj < 2; ++bj) { const f32x4 v0 = acc[ai][bj][m][0], v1 = acc[ai][bj][m][1];
;                     u32x4 w; w.x = pk_bf16(v0[0], v0[1]); w.y = pk_bf16(v0[2], v0[3]); w.z = pk_bf16(v1[0], v1[1]); w.w = pk_bf16(v1[2], v1[3]);
;                     *(u32x4*)(rowp + bj * HALF) = w; } }
;     __device__ __forceinline__ bool operator()(f32x4 (&acc)[2][2][4][2], const Unit& u, int wr, int wc, int fr, int fq) const {
;         if (u.type == 0) return d(acc, u, wr, wc, fr, fq);
;         if (u.kh == 0) return false;
;         return e(acc, u, wr, wc, fr, fq);
.Lkepi_sc:
	s_waitcnt lgkmcnt(0)
	s_cmp_lg_u32 s57, 0
	s_cselect_b64 s[34:35], -1, 0
	s_cmp_eq_u32 s57, 0
	s_cbranch_scc1 .LBB0_990
	v_lshl_or_b32 v146, s58, 8, v143
	v_lshl_add_u32 v145, s56, 8, v1
	v_ashrrev_i32_e32 v147, 31, v146
	v_mov_b64_e32 v[150:151], s[26:27]
	v_mad_i64_i32 v[148:149], s[0:1], v145, s52, v[150:151]
	v_lshlrev_b64 v[152:153], 1, v[146:147]
	v_lshl_add_u64 v[154:155], v[148:149], 0, v[152:153]
	v_cvt_pk_bf16_f32 v146, v126, v127
	v_cvt_pk_bf16_f32 v147, v128, v129
	v_cvt_pk_bf16_f32 v148, v122, v123
	v_cvt_pk_bf16_f32 v149, v124, v125
	global_store_dwordx4 v[154:155], v[146:149], off
	s_nop 1
	v_cvt_pk_bf16_f32 v146, v94, v95
	v_cvt_pk_bf16_f32 v147, v96, v97
	v_cvt_pk_bf16_f32 v148, v90, v91
	v_cvt_pk_bf16_f32 v149, v92, v93
	global_store_dwordx4 v[154:155], v[146:149], off offset:256
	s_nop 1
	v_or_b32_e32 v146, 16, v145
	v_mad_i64_i32 v[146:147], s[0:1], v146, s52, v[150:151]
	v_lshl_add_u64 v[154:155], v[146:147], 0, v[152:153]
	v_cvt_pk_bf16_f32 v146, v118, v119
	v_cvt_pk_bf16_f32 v147, v120, v121
	v_cvt_pk_bf16_f32 v148, v114, v115
	v_cvt_pk_bf16_f32 v149, v116, v117
	global_store_dwordx4 v[154:155], v[146:149], off
	s_nop 1
	v_cvt_pk_bf16_f32 v146, v86, v87
	v_cvt_pk_bf16_f32 v147, v88, v89
	v_cvt_pk_bf16_f32 v148, v82, v83
	v_cvt_pk_bf16_f32 v149, v84, v85
	global_store_dwordx4 v[154:155], v[146:149], off offset:256
	s_nop 1
	v_or_b32_e32 v146, 32, v145
	v_mad_i64_i32 v[146:147], s[0:1], v146, s52, v[150:151]
	v_lshl_add_u64 v[154:155], v[146:147], 0, v[152:153]
	v_cvt_pk_bf16_f32 v146, v110, v111
	v_cvt_pk_bf16_f32 v147, v112, v113
	v_cvt_pk_bf16_f32 v148, v106, v107
	v_cvt_pk_bf16_f32 v149, v108, v109
	global_store_dwordx4 v[154:155], v[146:149], off
	s_nop 1
	v_cvt_pk_bf16_f32 v146, v78, v79
	v_cvt_pk_bf16_f32 v147, v80, v81
	v_cvt_pk_bf16_f32 v148, v74, v75
	v_cvt_pk_bf16_f32 v149, v76, v77
	global_store_dwordx4 v[154:155], v[146:149], off offset:256
	s_nop 1
	v_or_b32_e32 v146, 48, v145
	v_mad_i64_i32 v[146:147], s[0:1], v146, s52, v[150:151]
	v_lshl_add_u64 v[154:155], v[146:147], 0, v[152:153]
	v_cvt_pk_bf16_f32 v146, v102, v103
	v_cvt_pk_bf16_f32 v147, v104, v105
	v_cvt_pk_bf16_f32 v148, v98, v99
	v_cvt_pk_bf16_f32 v149, v100, v101
	global_store_dwordx4 v[154:155], v[146:149], off
	s_nop 1
	v_cvt_pk_bf16_f32 v146, v70, v71
	v_cvt_pk_bf16_f32 v147, v72, v73
	v_cvt_pk_bf16_f32 v148, v66, v67
	v_cvt_pk_bf16_f32 v149, v68, v69
	global_store_dwordx4 v[154:155], v[146:149], off offset:256
	s_nop 1
	v_add_u32_e32 v146, 0x80, v145
	v_mad_i64_i32 v[146:147], s[0:1], v146, s52, v[150:151]
	v_lshl_add_u64 v[154:155], v[146:147], 0, v[152:153]
	v_cvt_pk_bf16_f32 v146, v62, v63
	v_cvt_pk_bf16_f32 v147, v64, v65
	v_cvt_pk_bf16_f32 v148, v58, v59
	v_cvt_pk_bf16_f32 v149, v60, v61
	global_store_dwordx4 v[154:155], v[146:149], off
	s_nop 1
	v_cvt_pk_bf16_f32 v146, v30, v31
	v_cvt_pk_bf16_f32 v147, v32, v33
	v_cvt_pk_bf16_f32 v148, v26, v27
	v_cvt_pk_bf16_f32 v149, v28, v29
	global_store_dwordx4 v[154:155], v[146:149], off offset:256
	s_nop 1
	v_add_u32_e32 v146, 0x90, v145
	v_mad_i64_i32 v[146:147], s[0:1], v146, s52, v[150:151]
	v_lshl_add_u64 v[154:155], v[146:147], 0, v[152:153]
	v_cvt_pk_bf16_f32 v146, v54, v55
	v_cvt_pk_bf16_f32 v147, v56, v57
	v_cvt_pk_bf16_f32 v148, v50, v51
	v_cvt_pk_bf16_f32 v149, v52, v53
	global_store_dwordx4 v[154:155], v[146:149], off
	s_nop 1
	v_cvt_pk_bf16_f32 v146, v22, v23
	v_cvt_pk_bf16_f32 v147, v24, v25
	v_cvt_pk_bf16_f32 v148, v18, v19
	v_cvt_pk_bf16_f32 v149, v20, v21
	global_store_dwordx4 v[154:155], v[146:149], off offset:256
	s_nop 1
	v_add_u32_e32 v146, 0xa0, v145
	v_mad_i64_i32 v[146:147], s[0:1], v146, s52, v[150:151]
	v_lshl_add_u64 v[154:155], v[146:147], 0, v[152:153]
	v_cvt_pk_bf16_f32 v146, v46, v47
	v_cvt_pk_bf16_f32 v147, v48, v49
	v_cvt_pk_bf16_f32 v148, v42, v43
	v_cvt_pk_bf16_f32 v149, v44, v45
	global_store_dwordx4 v[154:155], v[146:149], off
	v_add_u32_e32 v145, 0xb0, v145
	s_nop 0
	v_cvt_pk_bf16_f32 v146, v14, v15
	v_cvt_pk_bf16_f32 v147, v16, v17
	v_cvt_pk_bf16_f32 v148, v10, v11
	v_cvt_pk_bf16_f32 v149, v12, v13
	global_store_dwordx4 v[154:155], v[146:149], off offset:256
	s_nop 1
	v_mad_i64_i32 v[146:147], s[0:1], v145, s52, v[150:151]
	v_lshl_add_u64 v[150:151], v[146:147], 0, v[152:153]
	v_cvt_pk_bf16_f32 v146, v38, v39
	v_cvt_pk_bf16_f32 v147, v40, v41
	v_cvt_pk_bf16_f32 v148, v34, v35
	v_cvt_pk_bf16_f32 v149, v36, v37
	global_store_dwordx4 v[150:151], v[146:149], off
	s_nop 1
	v_cvt_pk_bf16_f32 v146, v6, v7
	v_cvt_pk_bf16_f32 v147, v8, v9
	v_cvt_pk_bf16_f32 v148, v2, v3
	v_cvt_pk_bf16_f32 v149, v4, v5
	global_store_dwordx4 v[150:151], v[146:149], off offset:256

; #define G_STAGE(bufoff, gbase, voff) do { _Pragma("unroll") for (int _i = 0; _i < 2; ++_i) \
;         __builtin_amdgcn_global_load_lds((const unsigned*)((const char*)(gbase) + (voff)[_i]), (LAS unsigned*)(lds + (bufoff) + ldsw + _i * 8192), 16, 0, 0); } while (0)
; #define G_WAIT_V(n) asm volatile("s_waitcnt vmcnt(" #n ")" ::: "memory")
; #define G_WAIT_L(n) asm volatile("s_waitcnt lgkmcnt(" #n ")" ::: "memory")
; #define G_BAR __builtin_amdgcn_s_barrier()
; #define G_SCHED __builtin_amdgcn_sched_barrier(0)
; template <int MODE  , class Epi, class Sched>
; __device__ __forceinline__ void gemm_phase(LAS unsigned char* lds, const GemmDesc g, const Sched& S, const Epi& E) {
;     ...
;             G_LDB(B0, 0, 0); G_SCHED; G_LDA(At, 0, 0); G_STAGE(G_SA(1, 1), a1 + hstepA, voffA);
;             G_WAIT_L(8); G_BAR; G_WAIT_L(0); G_MMA(0, 0, At, B0); G_BAR; G_SCHED;
;             G_LDB(B1, 0, 1); G_STAGE(G_SB(0, 0), b2, voffB);
;             G_BAR; G_WAIT_L(0); G_MMA(0, 1, At, B1); G_BAR;
;             G_LDA(At, 0, 1); G_STAGE(G_SA(0, 0), a2, voffA);
;             G_BAR; G_WAIT_L(0); G_MMA(1, 0, At, B0); G_BAR; G_SCHED;
;             G_STAGE(G_SB(0, 1), b2 + hstepB, voffB);
;             G_WAIT_V(6); G_BAR; G_MMA(1, 1, At, B1); G_BAR;
;             G_LDB(B0, 1, 0); G_SCHED; G_LDA(At, 1, 0); G_STAGE(G_SA(0, 1), a2 + hstepA, voffA);
.Lnodb_s1a:
	ds_read_b128 v[232:235], v163
	ds_read_b128 v[236:239], v163 offset:1024
	ds_read_b128 v[240:243], v163 offset:2048
	ds_read_b128 v[244:247], v163 offset:3072
.LBB0_1017:
	s_add_u32 s4, s2, 0x100
	s_addc_u32 s5, s3, 0
	s_cmp_eq_u32 s87, 28
	s_cselect_b32 s53, s47, s5
	s_cselect_b32 s52, s46, s4
	s_cselect_b32 s51, s49, s86
	s_cselect_b32 s50, s48, s85
	s_add_u32 s98, s2, 0x84080
	s_addc_u32 s99, s3, 0
	s_add_i32 m0, s58, 0xc000
	ds_read_b128 v[174:177], v164
	ds_read_b128 v[178:181], v164 offset:1024
	ds_read_b128 v[182:185], v164 offset:2048
	ds_read_b128 v[186:189], v164 offset:3072
	ds_read_b128 v[192:195], v164 offset:4096
	ds_read_b128 v[196:199], v164 offset:5120
	ds_read_b128 v[200:203], v164 offset:6144
	ds_read_b128 v[204:207], v164 offset:7168
	global_load_lds_dwordx4 v138, s[98:99]
	s_add_i32 m0, s58, 0xe000
	s_nop 0
	global_load_lds_dwordx4 v142, s[98:99]
	s_waitcnt lgkmcnt(8)
	s_barrier
	s_waitcnt lgkmcnt(0)
	s_setprio 1
	s_waitcnt lgkmcnt(0)
	v_mfma_f32_16x16x32_bf16 v[126:129], v[232:235], v[174:177], v[126:129]
	v_mfma_f32_16x16x32_bf16 v[122:125], v[240:243], v[174:177], v[122:125]
	v_mfma_f32_16x16x32_bf16 v[110:113], v[232:235], v[182:185], v[110:113]
	v_mfma_f32_16x16x32_bf16 v[106:109], v[240:243], v[182:185], v[106:109]
	v_mfma_f32_16x16x32_bf16 v[94:97], v[232:235], v[192:195], v[94:97]
	v_mfma_f32_16x16x32_bf16 v[90:93], v[240:243], v[192:195], v[90:93]
	v_mfma_f32_16x16x32_bf16 v[78:81], v[232:235], v[200:203], v[78:81]
	v_mfma_f32_16x16x32_bf16 v[74:77], v[240:243], v[200:203], v[74:77]
	v_mfma_f32_16x16x32_bf16 v[126:129], v[236:239], v[178:181], v[126:129]
	v_mfma_f32_16x16x32_bf16 v[122:125], v[244:247], v[178:181], v[122:125]
	v_mfma_f32_16x16x32_bf16 v[110:113], v[236:239], v[186:189], v[110:113]
	v_mfma_f32_16x16x32_bf16 v[106:109], v[244:247], v[186:189], v[106:109]
	v_mfma_f32_16x16x32_bf16 v[94:97], v[236:239], v[196:199], v[94:97]
	v_mfma_f32_16x16x32_bf16 v[90:93], v[244:247], v[196:199], v[90:93]
	v_mfma_f32_16x16x32_bf16 v[78:81], v[236:239], v[204:207], v[78:81]
	v_mfma_f32_16x16x32_bf16 v[74:77], v[244:247], v[204:207], v[74:77]
	s_setprio 0
	s_barrier
	s_add_i32 s0, s66, s57
	s_mov_b32 m0, s0
	ds_read_b128 v[208:211], v165
	ds_read_b128 v[212:215], v165 offset:1024
	ds_read_b128 v[216:219], v165 offset:2048
	ds_read_b128 v[220:223], v165 offset:3072
	global_load_lds_dwordx4 v140, s[50:51]
	s_add_i32 m0, s0, 0x2000
	s_nop 0
	global_load_lds_dwordx4 v144, s[50:51]
	s_barrier
	s_waitcnt lgkmcnt(0)
	s_setprio 1
	s_waitcnt lgkmcnt(0)
	v_mfma_f32_16x16x32_bf16 v[118:121], v[208:211], v[174:177], v[118:121]
	v_mfma_f32_16x16x32_bf16 v[114:117], v[216:219], v[174:177], v[114:117]
	v_mfma_f32_16x16x32_bf16 v[102:105], v[208:211], v[182:185], v[102:105]
	v_mfma_f32_16x16x32_bf16 v[98:101], v[216:219], v[182:185], v[98:101]
	v_mfma_f32_16x16x32_bf16 v[86:89], v[208:211], v[192:195], v[86:89]
	v_mfma_f32_16x16x32_bf16 v[82:85], v[216:219], v[192:195], v[82:85]
	v_mfma_f32_16x16x32_bf16 v[70:73], v[208:211], v[200:203], v[70:73]
	v_mfma_f32_16x16x32_bf16 v[66:69], v[216:219], v[200:203], v[66:69]
	v_mfma_f32_16x16x32_bf16 v[118:121], v[212:215], v[178:181], v[118:121]
	v_mfma_f32_16x16x32_bf16 v[114:117], v[220:223], v[178:181], v[114:117]
	v_mfma_f32_16x16x32_bf16 v[102:105], v[212:215], v[186:189], v[102:105]
	v_mfma_f32_16x16x32_bf16 v[98:101], v[220:223], v[186:189], v[98:101]
	v_mfma_f32_16x16x32_bf16 v[86:89], v[212:215], v[196:199], v[86:89]
	v_mfma_f32_16x16x32_bf16 v[82:85], v[220:223], v[196:199], v[82:85]
	v_mfma_f32_16x16x32_bf16 v[70:73], v[212:215], v[204:207], v[70:73]
	v_mfma_f32_16x16x32_bf16 v[66:69], v[220:223], v[204:207], v[66:69]
	s_setprio 0
	s_mov_b32 m0, s58
	s_barrier
	ds_read_b128 v[174:177], v164 offset:16384
	ds_read_b128 v[178:181], v164 offset:17408
	ds_read_b128 v[182:185], v164 offset:18432
	ds_read_b128 v[186:189], v164 offset:19456
	ds_read_b128 v[192:195], v164 offset:20480
	ds_read_b128 v[196:199], v164 offset:21504
	ds_read_b128 v[200:203], v164 offset:22528
	ds_read_b128 v[204:207], v164 offset:23552
	global_load_lds_dwordx4 v138, s[52:53]
	s_mov_b32 m0, s59
	s_nop 0
	global_load_lds_dwordx4 v142, s[52:53]
	s_waitcnt vmcnt(10)
	s_barrier
	s_waitcnt lgkmcnt(0)
	s_setprio 1
	s_waitcnt lgkmcnt(0)
	v_mfma_f32_16x16x32_bf16 v[62:65], v[232:235], v[174:177], v[62:65]
	v_mfma_f32_16x16x32_bf16 v[58:61], v[240:243], v[174:177], v[58:61]
	v_mfma_f32_16x16x32_bf16 v[46:49], v[232:235], v[182:185], v[46:49]
	v_mfma_f32_16x16x32_bf16 v[42:45], v[240:243], v[182:185], v[42:45]
	v_mfma_f32_16x16x32_bf16 v[30:33], v[232:235], v[192:195], v[30:33]
	v_mfma_f32_16x16x32_bf16 v[26:29], v[240:243], v[192:195], v[26:29]
	v_mfma_f32_16x16x32_bf16 v[14:17], v[232:235], v[200:203], v[14:17]
	v_mfma_f32_16x16x32_bf16 v[10:13], v[240:243], v[200:203], v[10:13]
	v_mfma_f32_16x16x32_bf16 v[62:65], v[236:239], v[178:181], v[62:65]
	v_mfma_f32_16x16x32_bf16 v[58:61], v[244:247], v[178:181], v[58:61]
	v_mfma_f32_16x16x32_bf16 v[46:49], v[236:239], v[186:189], v[46:49]
	v_mfma_f32_16x16x32_bf16 v[42:45], v[244:247], v[186:189], v[42:45]
	v_mfma_f32_16x16x32_bf16 v[30:33], v[236:239], v[196:199], v[30:33]
	v_mfma_f32_16x16x32_bf16 v[26:29], v[244:247], v[196:199], v[26:29]
	v_mfma_f32_16x16x32_bf16 v[14:17], v[236:239], v[204:207], v[14:17]
	v_mfma_f32_16x16x32_bf16 v[10:13], v[244:247], v[204:207], v[10:13]
	s_setprio 0
	s_barrier
	v_add_u32_e32 v146, 0x18000, v160
	ds_read_b128 v[130:133], v146
	ds_read_b128 v[134:137], v146 offset:1024
	ds_read_b128 v[154:157], v146 offset:2048
	ds_read_b128 v[170:173], v146 offset:3072
	s_add_u32 s0, s50, 0x84000
	s_addc_u32 s1, s51, 0
	s_add_i32 s2, s67, s57
	s_mov_b32 m0, s2
	s_nop 0
	global_load_lds_dwordx4 v140, s[0:1]
	s_add_i32 m0, s2, 0x2000
	s_nop 0
	global_load_lds_dwordx4 v144, s[0:1]
	s_waitcnt vmcnt(6)
	s_barrier
; #define G_STAGE(bufoff, gbase, voff) do { _Pragma("unroll") for (int _i = 0; _i < 2; ++_i) \
;         __builtin_amdgcn_global_load_lds((const unsigned*)((const char*)(gbase) + (voff)[_i]), (LAS unsigned*)(lds + (bufoff) + ldsw + _i * 8192), 16, 0, 0); } while (0)
; #define G_WAIT_L(n) asm volatile("s_waitcnt lgkmcnt(" #n ")" ::: "memory")
; #define G_BAR __builtin_amdgcn_s_barrier()
; #define G_SCHED __builtin_amdgcn_sched_barrier(0)
; template <int MODE  , class Epi, class Sched>
; __device__ __forceinline__ void gemm_phase(LAS unsigned char* lds, const GemmDesc g, const Sched& S, const Epi& E) {
;     ...
;             G_LDB(B0, 1, 0); G_SCHED; G_LDA(At, 1, 0); G_STAGE(G_SA(0, 1), a2 + hstepA, voffA);
;             G_WAIT_L(8); G_BAR; G_WAIT_L(0); G_MMA(0, 0, At, B0); G_BAR; G_SCHED;
;             G_LDB(B1, 1, 1); G_STAGE(G_SB(1, 0), b3, voffB);
;             G_BAR; G_WAIT_L(0); G_MMA(0, 1, At, B1); G_BAR;
;             G_LDA(At, 1, 1); G_STAGE(G_SA(1, 0), a3, voffA);
	s_setprio 1
	v_mfma_f32_16x16x32_bf16 v[54:57], v[208:211], v[174:177], v[54:57]
	v_mfma_f32_16x16x32_bf16 v[50:53], v[216:219], v[174:177], v[50:53]
	v_mfma_f32_16x16x32_bf16 v[38:41], v[208:211], v[182:185], v[38:41]
	v_mfma_f32_16x16x32_bf16 v[34:37], v[216:219], v[182:185], v[34:37]
	v_mfma_f32_16x16x32_bf16 v[22:25], v[208:211], v[192:195], v[22:25]
	v_mfma_f32_16x16x32_bf16 v[18:21], v[216:219], v[192:195], v[18:21]
	v_mfma_f32_16x16x32_bf16 v[6:9], v[208:211], v[200:203], v[6:9]
	v_mfma_f32_16x16x32_bf16 v[2:5], v[216:219], v[200:203], v[2:5]
	v_mfma_f32_16x16x32_bf16 v[54:57], v[212:215], v[178:181], v[54:57]
	v_mfma_f32_16x16x32_bf16 v[50:53], v[220:223], v[178:181], v[50:53]
	v_mfma_f32_16x16x32_bf16 v[38:41], v[212:215], v[186:189], v[38:41]
	v_mfma_f32_16x16x32_bf16 v[34:37], v[220:223], v[186:189], v[34:37]
	v_mfma_f32_16x16x32_bf16 v[22:25], v[212:215], v[196:199], v[22:25]
	v_mfma_f32_16x16x32_bf16 v[18:21], v[220:223], v[196:199], v[18:21]
	v_mfma_f32_16x16x32_bf16 v[6:9], v[212:215], v[204:207], v[6:9]
	v_mfma_f32_16x16x32_bf16 v[2:5], v[220:223], v[204:207], v[2:5]
	s_setprio 0
	s_add_i32 s2, 0, 0x18000
	s_barrier
	s_add_u32 s0, s52, 0x84000
	s_addc_u32 s1, s53, 0
	s_mov_b32 m0, s60
	ds_read_b128 v[174:177], v164 offset:32768
	ds_read_b128 v[178:181], v164 offset:33792
	ds_read_b128 v[182:185], v164 offset:34816
	ds_read_b128 v[186:189], v164 offset:35840
	ds_read_b128 v[192:195], v164 offset:36864
	ds_read_b128 v[196:199], v164 offset:37888
	ds_read_b128 v[200:203], v164 offset:38912
	ds_read_b128 v[204:207], v164 offset:39936
	global_load_lds_dwordx4 v138, s[0:1]
	s_mov_b32 m0, s61
	s_nop 0
	global_load_lds_dwordx4 v142, s[0:1]
	s_waitcnt lgkmcnt(8)
	s_barrier
	s_waitcnt lgkmcnt(0)
	s_setprio 1
	s_waitcnt lgkmcnt(0)
	v_mfma_f32_16x16x32_bf16 v[126:129], v[130:133], v[174:177], v[126:129]
	v_mfma_f32_16x16x32_bf16 v[122:125], v[154:157], v[174:177], v[122:125]
	v_mfma_f32_16x16x32_bf16 v[110:113], v[130:133], v[182:185], v[110:113]
	v_mfma_f32_16x16x32_bf16 v[106:109], v[154:157], v[182:185], v[106:109]
	v_mfma_f32_16x16x32_bf16 v[94:97], v[130:133], v[192:195], v[94:97]
	v_mfma_f32_16x16x32_bf16 v[90:93], v[154:157], v[192:195], v[90:93]
	v_mfma_f32_16x16x32_bf16 v[78:81], v[130:133], v[200:203], v[78:81]
	v_mfma_f32_16x16x32_bf16 v[74:77], v[154:157], v[200:203], v[74:77]
	v_mfma_f32_16x16x32_bf16 v[126:129], v[134:137], v[178:181], v[126:129]
	v_mfma_f32_16x16x32_bf16 v[122:125], v[170:173], v[178:181], v[122:125]
	v_mfma_f32_16x16x32_bf16 v[110:113], v[134:137], v[186:189], v[110:113]
	v_mfma_f32_16x16x32_bf16 v[106:109], v[170:173], v[186:189], v[106:109]
	v_mfma_f32_16x16x32_bf16 v[94:97], v[134:137], v[196:199], v[94:97]
	v_mfma_f32_16x16x32_bf16 v[90:93], v[170:173], v[196:199], v[90:93]
	v_mfma_f32_16x16x32_bf16 v[78:81], v[134:137], v[204:207], v[78:81]
	v_mfma_f32_16x16x32_bf16 v[74:77], v[170:173], v[204:207], v[74:77]
	s_setprio 0
	s_barrier
	s_add_i32 s3, 0, 0x1c000
	s_add_i32 s0, s2, s57
	v_add_u32_e32 v146, s3, v160
	s_add_u32 s98, s50, 0x80
	s_addc_u32 s99, s51, 0
	s_mov_b32 m0, s0
	ds_read_b128 v[208:211], v146
	ds_read_b128 v[212:215], v146 offset:1024
	ds_read_b128 v[216:219], v146 offset:2048
	ds_read_b128 v[220:223], v146 offset:3072
	global_load_lds_dwordx4 v140, s[98:99]
	s_add_i32 m0, s0, 0x2000
	s_nop 0
	global_load_lds_dwordx4 v144, s[98:99]
	s_barrier
	s_waitcnt lgkmcnt(0)
	s_setprio 1
	s_waitcnt lgkmcnt(0)
	v_mfma_f32_16x16x32_bf16 v[118:121], v[208:211], v[174:177], v[118:121]
	v_mfma_f32_16x16x32_bf16 v[114:117], v[216:219], v[174:177], v[114:117]
	v_mfma_f32_16x16x32_bf16 v[102:105], v[208:211], v[182:185], v[102:105]
	v_mfma_f32_16x16x32_bf16 v[98:101], v[216:219], v[182:185], v[98:101]
	v_mfma_f32_16x16x32_bf16 v[86:89], v[208:211], v[192:195], v[86:89]
	v_mfma_f32_16x16x32_bf16 v[82:85], v[216:219], v[192:195], v[82:85]
	v_mfma_f32_16x16x32_bf16 v[70:73], v[208:211], v[200:203], v[70:73]
	v_mfma_f32_16x16x32_bf16 v[66:69], v[216:219], v[200:203], v[66:69]
	v_mfma_f32_16x16x32_bf16 v[118:121], v[212:215], v[178:181], v[118:121]
	v_mfma_f32_16x16x32_bf16 v[114:117], v[220:223], v[178:181], v[114:117]
	v_mfma_f32_16x16x32_bf16 v[102:105], v[212:215], v[186:189], v[102:105]
	v_mfma_f32_16x16x32_bf16 v[98:101], v[220:223], v[186:189], v[98:101]
	v_mfma_f32_16x16x32_bf16 v[86:89], v[212:215], v[196:199], v[86:89]
	v_mfma_f32_16x16x32_bf16 v[82:85], v[220:223], v[196:199], v[82:85]
	v_mfma_f32_16x16x32_bf16 v[70:73], v[212:215], v[204:207], v[70:73]
	v_mfma_f32_16x16x32_bf16 v[66:69], v[220:223], v[204:207], v[66:69]
	s_setprio 0
	s_mov_b32 m0, s64
	s_add_u32 s98, s52, 0x80
	s_addc_u32 s99, s53, 0
	s_barrier
; #define G_STAGE(bufoff, gbase, voff) do { _Pragma("unroll") for (int _i = 0; _i < 2; ++_i) \
;         __builtin_amdgcn_global_load_lds((const unsigned*)((const char*)(gbase) + (voff)[_i]), (LAS unsigned*)(lds + (bufoff) + ldsw + _i * 8192), 16, 0, 0); } while (0)
; #define G_WAIT_V(n) asm volatile("s_waitcnt vmcnt(" #n ")" ::: "memory")
; #define G_WAIT_L(n) asm volatile("s_waitcnt lgkmcnt(" #n ")" ::: "memory")
; #define G_BAR __builtin_amdgcn_s_barrier()
; #define G_SCHED __builtin_amdgcn_sched_barrier(0)
; template <int MODE  , class Epi, class Sched>
; __device__ __forceinline__ void gemm_phase(LAS unsigned char* lds, const GemmDesc g, const Sched& S, const Epi& E) {
;     ...
;             G_LDA(At, 1, 1); G_STAGE(G_SA(1, 0), a3, voffA);
;             G_BAR; G_WAIT_L(0); G_MMA(1, 0, At, B0); G_BAR; G_SCHED;
;             G_STAGE(G_SB(1, 1), b3 + hstepB, voffB);
;             G_WAIT_V(6); G_BAR; G_MMA(1, 1, At, B1); G_BAR;
;         }
	ds_read_b128 v[174:177], v164 offset:49152
	ds_read_b128 v[178:181], v164 offset:50176
	ds_read_b128 v[182:185], v164 offset:51200
	ds_read_b128 v[186:189], v164 offset:52224
	ds_read_b128 v[192:195], v164 offset:53248
	ds_read_b128 v[196:199], v164 offset:54272
	ds_read_b128 v[200:203], v164 offset:55296
	ds_read_b128 v[204:207], v164 offset:56320
	global_load_lds_dwordx4 v138, s[98:99]
	s_mov_b32 m0, s65
	s_nop 0
	global_load_lds_dwordx4 v142, s[98:99]
	s_waitcnt vmcnt(10)
	s_barrier
	s_waitcnt lgkmcnt(0)
	s_setprio 1
	s_waitcnt lgkmcnt(0)
	v_mfma_f32_16x16x32_bf16 v[62:65], v[130:133], v[174:177], v[62:65]
	v_mfma_f32_16x16x32_bf16 v[58:61], v[154:157], v[174:177], v[58:61]
	v_mfma_f32_16x16x32_bf16 v[46:49], v[130:133], v[182:185], v[46:49]
	v_mfma_f32_16x16x32_bf16 v[42:45], v[154:157], v[182:185], v[42:45]
	v_mfma_f32_16x16x32_bf16 v[30:33], v[130:133], v[192:195], v[30:33]
	v_mfma_f32_16x16x32_bf16 v[26:29], v[154:157], v[192:195], v[26:29]
	v_mfma_f32_16x16x32_bf16 v[14:17], v[130:133], v[200:203], v[14:17]
	v_mfma_f32_16x16x32_bf16 v[10:13], v[154:157], v[200:203], v[10:13]
	v_mfma_f32_16x16x32_bf16 v[62:65], v[134:137], v[178:181], v[62:65]
	v_mfma_f32_16x16x32_bf16 v[58:61], v[170:173], v[178:181], v[58:61]
	v_mfma_f32_16x16x32_bf16 v[46:49], v[134:137], v[186:189], v[46:49]
	v_mfma_f32_16x16x32_bf16 v[42:45], v[170:173], v[186:189], v[42:45]
	v_mfma_f32_16x16x32_bf16 v[30:33], v[134:137], v[196:199], v[30:33]
	v_mfma_f32_16x16x32_bf16 v[26:29], v[170:173], v[196:199], v[26:29]
	v_mfma_f32_16x16x32_bf16 v[14:17], v[134:137], v[204:207], v[14:17]
	v_mfma_f32_16x16x32_bf16 v[10:13], v[170:173], v[204:207], v[10:13]
	s_setprio 0
	s_barrier
	ds_read_b128 v[232:235], v163
	ds_read_b128 v[236:239], v163 offset:1024
	ds_read_b128 v[240:243], v163 offset:2048
	ds_read_b128 v[244:247], v163 offset:3072
	s_add_u32 s0, s50, 0x84080
	s_addc_u32 s1, s51, 0
	s_add_i32 s2, s3, s57
	s_mov_b32 m0, s2
	s_nop 0
	global_load_lds_dwordx4 v140, s[0:1]
	s_add_i32 m0, s2, 0x2000
	s_nop 0
	global_load_lds_dwordx4 v144, s[0:1]
	s_waitcnt vmcnt(6)
	s_barrier
	s_setprio 1
	v_mfma_f32_16x16x32_bf16 v[54:57], v[208:211], v[174:177], v[54:57]
	s_add_i32 s87, s87, 2
	s_add_u32 s85, s85, 0x100
	s_addc_u32 s86, s86, 0
	s_cmp_gt_u32 s87, 29
	s_mov_b64 s[2:3], s[4:5]
	v_mfma_f32_16x16x32_bf16 v[50:53], v[216:219], v[174:177], v[50:53]
	v_mfma_f32_16x16x32_bf16 v[38:41], v[208:211], v[182:185], v[38:41]
	v_mfma_f32_16x16x32_bf16 v[34:37], v[216:219], v[182:185], v[34:37]
	v_mfma_f32_16x16x32_bf16 v[22:25], v[208:211], v[192:195], v[22:25]
	v_mfma_f32_16x16x32_bf16 v[18:21], v[216:219], v[192:195], v[18:21]
	v_mfma_f32_16x16x32_bf16 v[6:9], v[208:211], v[200:203], v[6:9]
	v_mfma_f32_16x16x32_bf16 v[2:5], v[216:219], v[200:203], v[2:5]
	v_mfma_f32_16x16x32_bf16 v[54:57], v[212:215], v[178:181], v[54:57]
	v_mfma_f32_16x16x32_bf16 v[50:53], v[220:223], v[178:181], v[50:53]
	v_mfma_f32_16x16x32_bf16 v[38:41], v[212:215], v[186:189], v[38:41]
	v_mfma_f32_16x16x32_bf16 v[34:37], v[220:223], v[186:189], v[34:37]
	v_mfma_f32_16x16x32_bf16 v[22:25], v[212:215], v[196:199], v[22:25]
	v_mfma_f32_16x16x32_bf16 v[18:21], v[220:223], v[196:199], v[18:21]
	v_mfma_f32_16x16x32_bf16 v[6:9], v[212:215], v[204:207], v[6:9]
	v_mfma_f32_16x16x32_bf16 v[2:5], v[220:223], v[204:207], v[2:5]
	s_setprio 0
	s_cbranch_scc1 .Lkdone_s1a
	s_barrier
	s_branch .LBB0_1017

; template <int MODE  , class Epi, class Sched>
; __device__ __forceinline__ void gemm_phase(LAS unsigned char* lds, const GemmDesc g, const Sched& S, const Epi& E) {
;     ...
;         const bool zero = E(acc, cur, wr, wc, fr, fq);
;     __device__ __forceinline__ bool operator()(f32x4 (&acc)[2][2][4][2], const Unit& u, int wr, int wc, int fr, int fq) const {
;         const int pn = u.pn, pmr = pn >= 40 ? (u.pm < 4 ? u.pm * 32 + 31 : 124 + u.pm) : u.pm, r0 = pmr * BM + wr * 64 + fr, cl = wc * 32 + fq * 8;
;         if (pn < 8) {
.Lkepi_s1a:
	s_waitcnt lgkmcnt(0)
	s_cmp_lt_i32 s81, 40
	s_cbranch_scc1 .LBB0_1024
	s_cmp_gt_i32 s84, 3
	s_mov_b64 s[2:3], -1
	s_cbranch_scc0 .LBB0_1021
	s_add_i32 s0, s84, 0x7c
	s_mov_b64 s[2:3], 0
